# as previous (merged 32-MFMA M-phase order) plus redundant post-barrier lgkmcnt(0) removed at the head of each M-phase
# speedup vs baseline: 1.0087x; 1.0043x over previous
.LBB0_1790:
	ds_read_b128 v[146:149], v159
	ds_read_b128 v[150:153], v159 offset:1024
	ds_read_b128 v[164:167], v159 offset:2048
	ds_read_b128 v[168:171], v159 offset:3072
	ds_read_b128 v[172:175], v160
	ds_read_b128 v[176:179], v160 offset:1024
	ds_read_b128 v[186:189], v160 offset:2048
	ds_read_b128 v[190:193], v160 offset:3072
	s_add_u32 s79, s6, 0xfff00080
	s_addc_u32 s80, s7, -1
	s_cmp_eq_u32 s78, 60
	s_cselect_b32 s91, s45, s80
	s_cselect_b32 s90, s74, s79
	s_cselect_b32 s89, s43, s77
	s_cselect_b32 s88, s75, s76
	s_add_i32 m0, s33, 0xc000
	ds_read_b128 v[194:197], v161
	ds_read_b128 v[198:201], v161 offset:1024
	ds_read_b128 v[202:205], v161 offset:2048
	ds_read_b128 v[206:209], v161 offset:3072
	ds_read_b128 v[210:213], v161 offset:4096
	ds_read_b128 v[214:217], v161 offset:5120
	ds_read_b128 v[218:221], v161 offset:6144
	ds_read_b128 v[222:225], v161 offset:7168
	global_load_lds_dwordx4 v138, s[6:7]
	s_add_i32 m0, s33, 0xe000
	s_nop 0
	global_load_lds_dwordx4 v140, s[6:7]
	s_waitcnt vmcnt(8)
	s_waitcnt lgkmcnt(0)
	s_barrier
	s_setprio 1
	v_mfma_f32_16x16x32_bf16 v[126:129], v[146:149], v[194:197], v[126:129]
	v_mfma_f32_16x16x32_bf16 v[126:129], v[150:153], v[198:201], v[126:129]
	v_mfma_f32_16x16x32_bf16 v[122:125], v[164:167], v[194:197], v[122:125]
	v_mfma_f32_16x16x32_bf16 v[122:125], v[168:171], v[198:201], v[122:125]
	v_mfma_f32_16x16x32_bf16 v[118:121], v[172:175], v[194:197], v[118:121]
	v_mfma_f32_16x16x32_bf16 v[118:121], v[176:179], v[198:201], v[118:121]
	v_mfma_f32_16x16x32_bf16 v[110:113], v[186:189], v[194:197], v[110:113]
	v_mfma_f32_16x16x32_bf16 v[110:113], v[190:193], v[198:201], v[110:113]
	v_mfma_f32_16x16x32_bf16 v[114:117], v[146:149], v[202:205], v[114:117]
	v_mfma_f32_16x16x32_bf16 v[114:117], v[150:153], v[206:209], v[114:117]
	v_mfma_f32_16x16x32_bf16 v[106:109], v[164:167], v[202:205], v[106:109]
	v_mfma_f32_16x16x32_bf16 v[106:109], v[168:171], v[206:209], v[106:109]
	v_mfma_f32_16x16x32_bf16 v[102:105], v[172:175], v[202:205], v[102:105]
	v_mfma_f32_16x16x32_bf16 v[102:105], v[176:179], v[206:209], v[102:105]
	v_mfma_f32_16x16x32_bf16 v[94:97], v[186:189], v[202:205], v[94:97]
	v_mfma_f32_16x16x32_bf16 v[94:97], v[190:193], v[206:209], v[94:97]
	v_mfma_f32_16x16x32_bf16 v[98:101], v[146:149], v[210:213], v[98:101]
	v_mfma_f32_16x16x32_bf16 v[98:101], v[150:153], v[214:217], v[98:101]
	v_mfma_f32_16x16x32_bf16 v[90:93], v[164:167], v[210:213], v[90:93]
	v_mfma_f32_16x16x32_bf16 v[90:93], v[168:171], v[214:217], v[90:93]
	v_mfma_f32_16x16x32_bf16 v[86:89], v[172:175], v[210:213], v[86:89]
	v_mfma_f32_16x16x32_bf16 v[86:89], v[176:179], v[214:217], v[86:89]
	v_mfma_f32_16x16x32_bf16 v[78:81], v[186:189], v[210:213], v[78:81]
	v_mfma_f32_16x16x32_bf16 v[78:81], v[190:193], v[214:217], v[78:81]
	v_mfma_f32_16x16x32_bf16 v[82:85], v[146:149], v[218:221], v[82:85]
	v_mfma_f32_16x16x32_bf16 v[82:85], v[150:153], v[222:225], v[82:85]
	v_mfma_f32_16x16x32_bf16 v[74:77], v[164:167], v[218:221], v[74:77]
	v_mfma_f32_16x16x32_bf16 v[74:77], v[168:171], v[222:225], v[74:77]
	v_mfma_f32_16x16x32_bf16 v[70:73], v[172:175], v[218:221], v[70:73]
	v_mfma_f32_16x16x32_bf16 v[70:73], v[176:179], v[222:225], v[70:73]
	v_mfma_f32_16x16x32_bf16 v[66:69], v[186:189], v[218:221], v[66:69]
	v_mfma_f32_16x16x32_bf16 v[66:69], v[190:193], v[222:225], v[66:69]
	s_setprio 0
	s_barrier
	s_add_i32 s79, s69, s25
	s_add_u32 s98, s88, 0x80
	s_addc_u32 s99, s89, 0
	s_mov_b32 m0, s79
	ds_read_b128 v[194:197], v161 offset:16384
	ds_read_b128 v[198:201], v161 offset:17408
	ds_read_b128 v[202:205], v161 offset:18432
	ds_read_b128 v[206:209], v161 offset:19456
	ds_read_b128 v[210:213], v161 offset:20480
	ds_read_b128 v[214:217], v161 offset:21504
	ds_read_b128 v[218:221], v161 offset:22528
	ds_read_b128 v[222:225], v161 offset:23552
	global_load_lds_dwordx4 v132, s[88:89]
	s_add_i32 m0, s79, 0x2000
	s_add_u32 s80, s88, 0x100000
	s_addc_u32 s81, s89, 0
	s_add_i32 s79, s70, s25
	global_load_lds_dwordx4 v136, s[88:89]
	s_mov_b32 m0, s79
	global_load_lds_dwordx4 v132, s[80:81]
	s_add_i32 m0, s79, 0x2000
	s_nop 0
	global_load_lds_dwordx4 v136, s[80:81]
	s_add_u32 s100, s90, 0x80
	s_addc_u32 s101, s91, 0
	s_mov_b32 m0, s33
	s_nop 0
	global_load_lds_dwordx4 v130, s[90:91]
	s_mov_b32 m0, s35
	s_nop 0
	global_load_lds_dwordx4 v134, s[90:91]
	s_waitcnt vmcnt(8)
	s_waitcnt lgkmcnt(0)
	s_barrier
	s_setprio 1
	v_mfma_f32_16x16x32_bf16 v[62:65], v[146:149], v[194:197], v[62:65]
	v_mfma_f32_16x16x32_bf16 v[62:65], v[150:153], v[198:201], v[62:65]
	v_mfma_f32_16x16x32_bf16 v[58:61], v[164:167], v[194:197], v[58:61]
	v_mfma_f32_16x16x32_bf16 v[58:61], v[168:171], v[198:201], v[58:61]
	v_mfma_f32_16x16x32_bf16 v[54:57], v[172:175], v[194:197], v[54:57]
	v_mfma_f32_16x16x32_bf16 v[54:57], v[176:179], v[198:201], v[54:57]
	v_mfma_f32_16x16x32_bf16 v[46:49], v[186:189], v[194:197], v[46:49]
	v_mfma_f32_16x16x32_bf16 v[46:49], v[190:193], v[198:201], v[46:49]
	v_mfma_f32_16x16x32_bf16 v[50:53], v[146:149], v[202:205], v[50:53]
	v_mfma_f32_16x16x32_bf16 v[50:53], v[150:153], v[206:209], v[50:53]
	v_mfma_f32_16x16x32_bf16 v[42:45], v[164:167], v[202:205], v[42:45]
	v_mfma_f32_16x16x32_bf16 v[42:45], v[168:171], v[206:209], v[42:45]
	v_mfma_f32_16x16x32_bf16 v[38:41], v[172:175], v[202:205], v[38:41]
	v_mfma_f32_16x16x32_bf16 v[38:41], v[176:179], v[206:209], v[38:41]
	v_mfma_f32_16x16x32_bf16 v[30:33], v[186:189], v[202:205], v[30:33]
	v_mfma_f32_16x16x32_bf16 v[30:33], v[190:193], v[206:209], v[30:33]
	v_mfma_f32_16x16x32_bf16 v[34:37], v[146:149], v[210:213], v[34:37]
	v_mfma_f32_16x16x32_bf16 v[34:37], v[150:153], v[214:217], v[34:37]
	v_mfma_f32_16x16x32_bf16 v[26:29], v[164:167], v[210:213], v[26:29]
	v_mfma_f32_16x16x32_bf16 v[26:29], v[168:171], v[214:217], v[26:29]
	v_mfma_f32_16x16x32_bf16 v[22:25], v[172:175], v[210:213], v[22:25]
	v_mfma_f32_16x16x32_bf16 v[22:25], v[176:179], v[214:217], v[22:25]
	v_mfma_f32_16x16x32_bf16 v[14:17], v[186:189], v[210:213], v[14:17]
	v_mfma_f32_16x16x32_bf16 v[14:17], v[190:193], v[214:217], v[14:17]
	v_mfma_f32_16x16x32_bf16 v[18:21], v[146:149], v[218:221], v[18:21]
	v_mfma_f32_16x16x32_bf16 v[18:21], v[150:153], v[222:225], v[18:21]
	v_mfma_f32_16x16x32_bf16 v[10:13], v[164:167], v[218:221], v[10:13]
	v_mfma_f32_16x16x32_bf16 v[10:13], v[168:171], v[222:225], v[10:13]
	v_mfma_f32_16x16x32_bf16 v[6:9], v[172:175], v[218:221], v[6:9]
	v_mfma_f32_16x16x32_bf16 v[6:9], v[176:179], v[222:225], v[6:9]
	v_mfma_f32_16x16x32_bf16 v[2:5], v[186:189], v[218:221], v[2:5]
	v_mfma_f32_16x16x32_bf16 v[2:5], v[190:193], v[222:225], v[2:5]
	s_setprio 0
	s_barrier
	s_add_i32 s79, 0, 0x18000
	s_add_i32 s82, 0, 0x1c000
	v_add_u32_e32 v168, s79, v155
	v_add_u32_e32 v183, s82, v155
	ds_read_b128 v[146:149], v168
	ds_read_b128 v[150:153], v168 offset:1024
	ds_read_b128 v[164:167], v168 offset:2048
	ds_read_b128 v[168:171], v168 offset:3072
	ds_read_b128 v[172:175], v183
	ds_read_b128 v[176:179], v183 offset:1024
	ds_read_b128 v[186:189], v183 offset:2048
	ds_read_b128 v[190:193], v183 offset:3072
	s_add_u32 s80, s90, 0x100000
	s_addc_u32 s81, s91, 0
	s_mov_b32 m0, s59
	ds_read_b128 v[194:197], v161 offset:32768
	ds_read_b128 v[198:201], v161 offset:33792
	ds_read_b128 v[202:205], v161 offset:34816
	ds_read_b128 v[206:209], v161 offset:35840
	ds_read_b128 v[210:213], v161 offset:36864
	ds_read_b128 v[214:217], v161 offset:37888
	ds_read_b128 v[218:221], v161 offset:38912
	ds_read_b128 v[222:225], v161 offset:39936
	global_load_lds_dwordx4 v130, s[80:81]
	s_mov_b32 m0, s62
	s_nop 0
	global_load_lds_dwordx4 v134, s[80:81]
	s_waitcnt vmcnt(8)
	s_waitcnt lgkmcnt(0)
	s_barrier
	s_setprio 1
	v_mfma_f32_16x16x32_bf16 v[126:129], v[146:149], v[194:197], v[126:129]
	v_mfma_f32_16x16x32_bf16 v[126:129], v[150:153], v[198:201], v[126:129]
	v_mfma_f32_16x16x32_bf16 v[122:125], v[164:167], v[194:197], v[122:125]
	v_mfma_f32_16x16x32_bf16 v[122:125], v[168:171], v[198:201], v[122:125]
	v_mfma_f32_16x16x32_bf16 v[118:121], v[172:175], v[194:197], v[118:121]
	v_mfma_f32_16x16x32_bf16 v[118:121], v[176:179], v[198:201], v[118:121]
	v_mfma_f32_16x16x32_bf16 v[110:113], v[186:189], v[194:197], v[110:113]
	v_mfma_f32_16x16x32_bf16 v[110:113], v[190:193], v[198:201], v[110:113]
	v_mfma_f32_16x16x32_bf16 v[114:117], v[146:149], v[202:205], v[114:117]
	v_mfma_f32_16x16x32_bf16 v[114:117], v[150:153], v[206:209], v[114:117]
	v_mfma_f32_16x16x32_bf16 v[106:109], v[164:167], v[202:205], v[106:109]
	v_mfma_f32_16x16x32_bf16 v[106:109], v[168:171], v[206:209], v[106:109]
	v_mfma_f32_16x16x32_bf16 v[102:105], v[172:175], v[202:205], v[102:105]
	v_mfma_f32_16x16x32_bf16 v[102:105], v[176:179], v[206:209], v[102:105]
	v_mfma_f32_16x16x32_bf16 v[94:97], v[186:189], v[202:205], v[94:97]
	v_mfma_f32_16x16x32_bf16 v[94:97], v[190:193], v[206:209], v[94:97]
	v_mfma_f32_16x16x32_bf16 v[98:101], v[146:149], v[210:213], v[98:101]
	v_mfma_f32_16x16x32_bf16 v[98:101], v[150:153], v[214:217], v[98:101]
	v_mfma_f32_16x16x32_bf16 v[90:93], v[164:167], v[210:213], v[90:93]
	v_mfma_f32_16x16x32_bf16 v[90:93], v[168:171], v[214:217], v[90:93]
	v_mfma_f32_16x16x32_bf16 v[86:89], v[172:175], v[210:213], v[86:89]
	v_mfma_f32_16x16x32_bf16 v[86:89], v[176:179], v[214:217], v[86:89]
	v_mfma_f32_16x16x32_bf16 v[78:81], v[186:189], v[210:213], v[78:81]
	v_mfma_f32_16x16x32_bf16 v[78:81], v[190:193], v[214:217], v[78:81]
	v_mfma_f32_16x16x32_bf16 v[82:85], v[146:149], v[218:221], v[82:85]
	v_mfma_f32_16x16x32_bf16 v[82:85], v[150:153], v[222:225], v[82:85]
	v_mfma_f32_16x16x32_bf16 v[74:77], v[164:167], v[218:221], v[74:77]
	v_mfma_f32_16x16x32_bf16 v[74:77], v[168:171], v[222:225], v[74:77]
	v_mfma_f32_16x16x32_bf16 v[70:73], v[172:175], v[218:221], v[70:73]
	v_mfma_f32_16x16x32_bf16 v[70:73], v[176:179], v[222:225], v[70:73]
	v_mfma_f32_16x16x32_bf16 v[66:69], v[186:189], v[218:221], v[66:69]
	v_mfma_f32_16x16x32_bf16 v[66:69], v[190:193], v[222:225], v[66:69]
	s_setprio 0
	s_barrier
	s_add_i32 s79, s79, s25
	s_mov_b32 m0, s79
	ds_read_b128 v[194:197], v161 offset:49152
	ds_read_b128 v[198:201], v161 offset:50176
	ds_read_b128 v[202:205], v161 offset:51200
	ds_read_b128 v[206:209], v161 offset:52224
	ds_read_b128 v[210:213], v161 offset:53248
	ds_read_b128 v[214:217], v161 offset:54272
	ds_read_b128 v[218:221], v161 offset:55296
	ds_read_b128 v[222:225], v161 offset:56320
	global_load_lds_dwordx4 v132, s[98:99]
	s_add_i32 m0, s79, 0x2000
	s_add_u32 s80, s88, 0x100080
	s_addc_u32 s81, s89, 0
	s_add_i32 s79, s82, s25
	global_load_lds_dwordx4 v136, s[98:99]
	s_mov_b32 m0, s79
	s_nop 0
	global_load_lds_dwordx4 v132, s[80:81]
	s_add_i32 m0, s79, 0x2000
	s_nop 0
	global_load_lds_dwordx4 v136, s[80:81]
	s_mov_b32 m0, s66
	s_nop 0
	global_load_lds_dwordx4 v130, s[100:101]
	s_mov_b32 m0, s67
	s_nop 0
	global_load_lds_dwordx4 v134, s[100:101]
	s_waitcnt vmcnt(8)
	s_waitcnt lgkmcnt(0)
	s_barrier
	s_setprio 1
	v_mfma_f32_16x16x32_bf16 v[62:65], v[146:149], v[194:197], v[62:65]
	v_mfma_f32_16x16x32_bf16 v[62:65], v[150:153], v[198:201], v[62:65]
	v_mfma_f32_16x16x32_bf16 v[58:61], v[164:167], v[194:197], v[58:61]
	v_mfma_f32_16x16x32_bf16 v[58:61], v[168:171], v[198:201], v[58:61]
	v_mfma_f32_16x16x32_bf16 v[54:57], v[172:175], v[194:197], v[54:57]
	v_mfma_f32_16x16x32_bf16 v[54:57], v[176:179], v[198:201], v[54:57]
	v_mfma_f32_16x16x32_bf16 v[46:49], v[186:189], v[194:197], v[46:49]
	v_mfma_f32_16x16x32_bf16 v[46:49], v[190:193], v[198:201], v[46:49]
	v_mfma_f32_16x16x32_bf16 v[50:53], v[146:149], v[202:205], v[50:53]
	v_mfma_f32_16x16x32_bf16 v[50:53], v[150:153], v[206:209], v[50:53]
	v_mfma_f32_16x16x32_bf16 v[42:45], v[164:167], v[202:205], v[42:45]
	v_mfma_f32_16x16x32_bf16 v[42:45], v[168:171], v[206:209], v[42:45]
	v_mfma_f32_16x16x32_bf16 v[38:41], v[172:175], v[202:205], v[38:41]
	v_mfma_f32_16x16x32_bf16 v[38:41], v[176:179], v[206:209], v[38:41]
	v_mfma_f32_16x16x32_bf16 v[30:33], v[186:189], v[202:205], v[30:33]
	v_mfma_f32_16x16x32_bf16 v[30:33], v[190:193], v[206:209], v[30:33]
	v_mfma_f32_16x16x32_bf16 v[34:37], v[146:149], v[210:213], v[34:37]
	v_mfma_f32_16x16x32_bf16 v[34:37], v[150:153], v[214:217], v[34:37]
	v_mfma_f32_16x16x32_bf16 v[26:29], v[164:167], v[210:213], v[26:29]
	v_mfma_f32_16x16x32_bf16 v[26:29], v[168:171], v[214:217], v[26:29]
	v_mfma_f32_16x16x32_bf16 v[22:25], v[172:175], v[210:213], v[22:25]
	v_mfma_f32_16x16x32_bf16 v[22:25], v[176:179], v[214:217], v[22:25]
	v_mfma_f32_16x16x32_bf16 v[14:17], v[186:189], v[210:213], v[14:17]
	v_mfma_f32_16x16x32_bf16 v[14:17], v[190:193], v[214:217], v[14:17]
	v_mfma_f32_16x16x32_bf16 v[18:21], v[146:149], v[218:221], v[18:21]
	v_mfma_f32_16x16x32_bf16 v[18:21], v[150:153], v[222:225], v[18:21]
	v_mfma_f32_16x16x32_bf16 v[10:13], v[164:167], v[218:221], v[10:13]
	v_mfma_f32_16x16x32_bf16 v[10:13], v[168:171], v[222:225], v[10:13]
	v_mfma_f32_16x16x32_bf16 v[6:9], v[172:175], v[218:221], v[6:9]
	v_mfma_f32_16x16x32_bf16 v[6:9], v[176:179], v[222:225], v[6:9]
	v_mfma_f32_16x16x32_bf16 v[2:5], v[186:189], v[218:221], v[2:5]
	v_mfma_f32_16x16x32_bf16 v[2:5], v[190:193], v[222:225], v[2:5]
	s_setprio 0
	s_barrier
	s_add_i32 s78, s78, 2
	s_add_u32 s6, s6, 0x100
	s_addc_u32 s7, s7, 0
	s_add_u32 s76, s76, 0x100
	s_addc_u32 s77, s77, 0
	s_cmp_gt_u32 s78, 61
	s_cbranch_scc0 .LBB0_1790
	s_and_b64 vcc, exec, s[40:41]
	s_cbranch_vccz .LBB0_1793
	s_barrier

.LBB0_2109:
	ds_read_b128 v[130:133], v155
	ds_read_b128 v[134:137], v155 offset:1024
	ds_read_b128 v[138:141], v155 offset:2048
	ds_read_b128 v[142:145], v155 offset:3072
	ds_read_b128 v[166:169], v176
	ds_read_b128 v[170:173], v176 offset:1024
	ds_read_b128 v[186:189], v176 offset:2048
	ds_read_b128 v[190:193], v176 offset:3072
	s_add_u32 s74, s50, 0xfff00080
	s_addc_u32 s75, s51, -1
	s_cmp_eq_u32 s73, 60
	s_cselect_b32 s85, s26, s75
	s_cselect_b32 s84, s45, s74
	s_cselect_b32 s83, s43, s72
	s_cselect_b32 s82, s70, s71
	s_add_i32 m0, s23, 0xc000
	ds_read_b128 v[194:197], v177
	ds_read_b128 v[198:201], v177 offset:1024
	ds_read_b128 v[202:205], v177 offset:2048
	ds_read_b128 v[206:209], v177 offset:3072
	ds_read_b128 v[210:213], v177 offset:4096
	ds_read_b128 v[214:217], v177 offset:5120
	ds_read_b128 v[218:221], v177 offset:6144
	ds_read_b128 v[222:225], v177 offset:7168
	global_load_lds_dwordx4 v158, s[50:51]
	s_add_i32 m0, s23, 0xe000
	s_nop 0
	global_load_lds_dwordx4 v160, s[50:51]
	s_waitcnt vmcnt(8)
	s_waitcnt lgkmcnt(0)
	s_barrier
	s_setprio 1
	v_mfma_f32_16x16x32_bf16 v[126:129], v[130:133], v[194:197], v[126:129]
	v_mfma_f32_16x16x32_bf16 v[126:129], v[134:137], v[198:201], v[126:129]
	v_mfma_f32_16x16x32_bf16 v[122:125], v[138:141], v[194:197], v[122:125]
	v_mfma_f32_16x16x32_bf16 v[122:125], v[142:145], v[198:201], v[122:125]
	v_mfma_f32_16x16x32_bf16 v[118:121], v[166:169], v[194:197], v[118:121]
	v_mfma_f32_16x16x32_bf16 v[118:121], v[170:173], v[198:201], v[118:121]
	v_mfma_f32_16x16x32_bf16 v[114:117], v[186:189], v[194:197], v[114:117]
	v_mfma_f32_16x16x32_bf16 v[114:117], v[190:193], v[198:201], v[114:117]
	v_mfma_f32_16x16x32_bf16 v[110:113], v[130:133], v[202:205], v[110:113]
	v_mfma_f32_16x16x32_bf16 v[110:113], v[134:137], v[206:209], v[110:113]
	v_mfma_f32_16x16x32_bf16 v[106:109], v[138:141], v[202:205], v[106:109]
	v_mfma_f32_16x16x32_bf16 v[106:109], v[142:145], v[206:209], v[106:109]
	v_mfma_f32_16x16x32_bf16 v[102:105], v[166:169], v[202:205], v[102:105]
	v_mfma_f32_16x16x32_bf16 v[102:105], v[170:173], v[206:209], v[102:105]
	v_mfma_f32_16x16x32_bf16 v[98:101], v[186:189], v[202:205], v[98:101]
	v_mfma_f32_16x16x32_bf16 v[98:101], v[190:193], v[206:209], v[98:101]
	v_mfma_f32_16x16x32_bf16 v[94:97], v[130:133], v[210:213], v[94:97]
	v_mfma_f32_16x16x32_bf16 v[94:97], v[134:137], v[214:217], v[94:97]
	v_mfma_f32_16x16x32_bf16 v[90:93], v[138:141], v[210:213], v[90:93]
	v_mfma_f32_16x16x32_bf16 v[90:93], v[142:145], v[214:217], v[90:93]
	v_mfma_f32_16x16x32_bf16 v[86:89], v[166:169], v[210:213], v[86:89]
	v_mfma_f32_16x16x32_bf16 v[86:89], v[170:173], v[214:217], v[86:89]
	v_mfma_f32_16x16x32_bf16 v[82:85], v[186:189], v[210:213], v[82:85]
	v_mfma_f32_16x16x32_bf16 v[82:85], v[190:193], v[214:217], v[82:85]
	v_mfma_f32_16x16x32_bf16 v[78:81], v[130:133], v[218:221], v[78:81]
	v_mfma_f32_16x16x32_bf16 v[78:81], v[134:137], v[222:225], v[78:81]
	v_mfma_f32_16x16x32_bf16 v[74:77], v[138:141], v[218:221], v[74:77]
	v_mfma_f32_16x16x32_bf16 v[74:77], v[142:145], v[222:225], v[74:77]
	v_mfma_f32_16x16x32_bf16 v[70:73], v[166:169], v[218:221], v[70:73]
	v_mfma_f32_16x16x32_bf16 v[70:73], v[170:173], v[222:225], v[70:73]
	v_mfma_f32_16x16x32_bf16 v[66:69], v[186:189], v[218:221], v[66:69]
	v_mfma_f32_16x16x32_bf16 v[66:69], v[190:193], v[222:225], v[66:69]
	s_setprio 0
	s_barrier
	s_add_i32 s74, s67, s3
	s_add_u32 s98, s82, 0x80
	s_addc_u32 s99, s83, 0
	s_mov_b32 m0, s74
	ds_read_b128 v[194:197], v177 offset:16384
	ds_read_b128 v[198:201], v177 offset:17408
	ds_read_b128 v[202:205], v177 offset:18432
	ds_read_b128 v[206:209], v177 offset:19456
	ds_read_b128 v[210:213], v177 offset:20480
	ds_read_b128 v[214:217], v177 offset:21504
	ds_read_b128 v[218:221], v177 offset:22528
	ds_read_b128 v[222:225], v177 offset:23552
	global_load_lds_dwordx4 v148, s[82:83]
	s_add_i32 m0, s74, 0x2000
	s_add_u32 s74, s82, 0x100000
	s_addc_u32 s75, s83, 0
	s_add_i32 s76, s68, s3
	global_load_lds_dwordx4 v152, s[82:83]
	s_mov_b32 m0, s76
	global_load_lds_dwordx4 v148, s[74:75]
	s_add_i32 m0, s76, 0x2000
	s_nop 0
	global_load_lds_dwordx4 v152, s[74:75]
	s_add_u32 s100, s84, 0x80
	s_addc_u32 s101, s85, 0
	s_mov_b32 m0, s23
	s_nop 0
	global_load_lds_dwordx4 v146, s[84:85]
	s_mov_b32 m0, s25
	s_nop 0
	global_load_lds_dwordx4 v150, s[84:85]
	s_waitcnt vmcnt(8)
	s_waitcnt lgkmcnt(0)
	s_barrier
	s_setprio 1
	v_mfma_f32_16x16x32_bf16 v[62:65], v[130:133], v[194:197], v[62:65]
	v_mfma_f32_16x16x32_bf16 v[62:65], v[134:137], v[198:201], v[62:65]
	v_mfma_f32_16x16x32_bf16 v[58:61], v[138:141], v[194:197], v[58:61]
	v_mfma_f32_16x16x32_bf16 v[58:61], v[142:145], v[198:201], v[58:61]
	v_mfma_f32_16x16x32_bf16 v[54:57], v[166:169], v[194:197], v[54:57]
	v_mfma_f32_16x16x32_bf16 v[54:57], v[170:173], v[198:201], v[54:57]
	v_mfma_f32_16x16x32_bf16 v[50:53], v[186:189], v[194:197], v[50:53]
	v_mfma_f32_16x16x32_bf16 v[50:53], v[190:193], v[198:201], v[50:53]
	v_mfma_f32_16x16x32_bf16 v[46:49], v[130:133], v[202:205], v[46:49]
	v_mfma_f32_16x16x32_bf16 v[46:49], v[134:137], v[206:209], v[46:49]
	v_mfma_f32_16x16x32_bf16 v[42:45], v[138:141], v[202:205], v[42:45]
	v_mfma_f32_16x16x32_bf16 v[42:45], v[142:145], v[206:209], v[42:45]
	v_mfma_f32_16x16x32_bf16 v[38:41], v[166:169], v[202:205], v[38:41]
	v_mfma_f32_16x16x32_bf16 v[38:41], v[170:173], v[206:209], v[38:41]
	v_mfma_f32_16x16x32_bf16 v[34:37], v[186:189], v[202:205], v[34:37]
	v_mfma_f32_16x16x32_bf16 v[34:37], v[190:193], v[206:209], v[34:37]
	v_mfma_f32_16x16x32_bf16 v[30:33], v[130:133], v[210:213], v[30:33]
	v_mfma_f32_16x16x32_bf16 v[30:33], v[134:137], v[214:217], v[30:33]
	v_mfma_f32_16x16x32_bf16 v[26:29], v[138:141], v[210:213], v[26:29]
	v_mfma_f32_16x16x32_bf16 v[26:29], v[142:145], v[214:217], v[26:29]
	v_mfma_f32_16x16x32_bf16 v[22:25], v[166:169], v[210:213], v[22:25]
	v_mfma_f32_16x16x32_bf16 v[22:25], v[170:173], v[214:217], v[22:25]
	v_mfma_f32_16x16x32_bf16 v[18:21], v[186:189], v[210:213], v[18:21]
	v_mfma_f32_16x16x32_bf16 v[18:21], v[190:193], v[214:217], v[18:21]
	v_mfma_f32_16x16x32_bf16 v[14:17], v[130:133], v[218:221], v[14:17]
	v_mfma_f32_16x16x32_bf16 v[14:17], v[134:137], v[222:225], v[14:17]
	v_mfma_f32_16x16x32_bf16 v[10:13], v[138:141], v[218:221], v[10:13]
	v_mfma_f32_16x16x32_bf16 v[10:13], v[142:145], v[222:225], v[10:13]
	v_mfma_f32_16x16x32_bf16 v[6:9], v[166:169], v[218:221], v[6:9]
	v_mfma_f32_16x16x32_bf16 v[6:9], v[170:173], v[222:225], v[6:9]
	v_mfma_f32_16x16x32_bf16 v[2:5], v[186:189], v[218:221], v[2:5]
	v_mfma_f32_16x16x32_bf16 v[2:5], v[190:193], v[222:225], v[2:5]
	s_setprio 0
	s_barrier
	s_add_i32 s76, 0, 0x18000
	s_add_i32 s77, 0, 0x1c000
	v_add_u32_e32 v142, s76, v174
	v_add_u32_e32 v179, s77, v174
	ds_read_b128 v[130:133], v142
	ds_read_b128 v[134:137], v142 offset:1024
	ds_read_b128 v[138:141], v142 offset:2048
	ds_read_b128 v[142:145], v142 offset:3072
	ds_read_b128 v[166:169], v179
	ds_read_b128 v[170:173], v179 offset:1024
	ds_read_b128 v[186:189], v179 offset:2048
	ds_read_b128 v[190:193], v179 offset:3072
	s_add_u32 s74, s84, 0x100000
	s_addc_u32 s75, s85, 0
	s_mov_b32 m0, s33
	ds_read_b128 v[194:197], v177 offset:32768
	ds_read_b128 v[198:201], v177 offset:33792
	ds_read_b128 v[202:205], v177 offset:34816
	ds_read_b128 v[206:209], v177 offset:35840
	ds_read_b128 v[210:213], v177 offset:36864
	ds_read_b128 v[214:217], v177 offset:37888
	ds_read_b128 v[218:221], v177 offset:38912
	ds_read_b128 v[222:225], v177 offset:39936
	global_load_lds_dwordx4 v146, s[74:75]
	s_mov_b32 m0, s35
	s_nop 0
	global_load_lds_dwordx4 v150, s[74:75]
	s_waitcnt vmcnt(8)
	s_waitcnt lgkmcnt(0)
	s_barrier
	s_setprio 1
	v_mfma_f32_16x16x32_bf16 v[126:129], v[130:133], v[194:197], v[126:129]
	v_mfma_f32_16x16x32_bf16 v[126:129], v[134:137], v[198:201], v[126:129]
	v_mfma_f32_16x16x32_bf16 v[122:125], v[138:141], v[194:197], v[122:125]
	v_mfma_f32_16x16x32_bf16 v[122:125], v[142:145], v[198:201], v[122:125]
	v_mfma_f32_16x16x32_bf16 v[118:121], v[166:169], v[194:197], v[118:121]
	v_mfma_f32_16x16x32_bf16 v[118:121], v[170:173], v[198:201], v[118:121]
	v_mfma_f32_16x16x32_bf16 v[114:117], v[186:189], v[194:197], v[114:117]
	v_mfma_f32_16x16x32_bf16 v[114:117], v[190:193], v[198:201], v[114:117]
	v_mfma_f32_16x16x32_bf16 v[110:113], v[130:133], v[202:205], v[110:113]
	v_mfma_f32_16x16x32_bf16 v[110:113], v[134:137], v[206:209], v[110:113]
	v_mfma_f32_16x16x32_bf16 v[106:109], v[138:141], v[202:205], v[106:109]
	v_mfma_f32_16x16x32_bf16 v[106:109], v[142:145], v[206:209], v[106:109]
	v_mfma_f32_16x16x32_bf16 v[102:105], v[166:169], v[202:205], v[102:105]
	v_mfma_f32_16x16x32_bf16 v[102:105], v[170:173], v[206:209], v[102:105]
	v_mfma_f32_16x16x32_bf16 v[98:101], v[186:189], v[202:205], v[98:101]
	v_mfma_f32_16x16x32_bf16 v[98:101], v[190:193], v[206:209], v[98:101]
	v_mfma_f32_16x16x32_bf16 v[94:97], v[130:133], v[210:213], v[94:97]
	v_mfma_f32_16x16x32_bf16 v[94:97], v[134:137], v[214:217], v[94:97]
	v_mfma_f32_16x16x32_bf16 v[90:93], v[138:141], v[210:213], v[90:93]
	v_mfma_f32_16x16x32_bf16 v[90:93], v[142:145], v[214:217], v[90:93]
	v_mfma_f32_16x16x32_bf16 v[86:89], v[166:169], v[210:213], v[86:89]
	v_mfma_f32_16x16x32_bf16 v[86:89], v[170:173], v[214:217], v[86:89]
	v_mfma_f32_16x16x32_bf16 v[82:85], v[186:189], v[210:213], v[82:85]
	v_mfma_f32_16x16x32_bf16 v[82:85], v[190:193], v[214:217], v[82:85]
	v_mfma_f32_16x16x32_bf16 v[78:81], v[130:133], v[218:221], v[78:81]
	v_mfma_f32_16x16x32_bf16 v[78:81], v[134:137], v[222:225], v[78:81]
	v_mfma_f32_16x16x32_bf16 v[74:77], v[138:141], v[218:221], v[74:77]
	v_mfma_f32_16x16x32_bf16 v[74:77], v[142:145], v[222:225], v[74:77]
	v_mfma_f32_16x16x32_bf16 v[70:73], v[166:169], v[218:221], v[70:73]
	v_mfma_f32_16x16x32_bf16 v[70:73], v[170:173], v[222:225], v[70:73]
	v_mfma_f32_16x16x32_bf16 v[66:69], v[186:189], v[218:221], v[66:69]
	v_mfma_f32_16x16x32_bf16 v[66:69], v[190:193], v[222:225], v[66:69]
	s_setprio 0
	s_barrier
	s_add_i32 s74, s76, s3
	s_mov_b32 m0, s74
	ds_read_b128 v[194:197], v177 offset:49152
	ds_read_b128 v[198:201], v177 offset:50176
	ds_read_b128 v[202:205], v177 offset:51200
	ds_read_b128 v[206:209], v177 offset:52224
	ds_read_b128 v[210:213], v177 offset:53248
	ds_read_b128 v[214:217], v177 offset:54272
	ds_read_b128 v[218:221], v177 offset:55296
	ds_read_b128 v[222:225], v177 offset:56320
	global_load_lds_dwordx4 v148, s[98:99]
	s_add_i32 m0, s74, 0x2000
	s_add_u32 s74, s82, 0x100080
	s_addc_u32 s75, s83, 0
	s_add_i32 s76, s77, s3
	global_load_lds_dwordx4 v152, s[98:99]
	s_mov_b32 m0, s76
	s_nop 0
	global_load_lds_dwordx4 v148, s[74:75]
	s_add_i32 m0, s76, 0x2000
	s_nop 0
	global_load_lds_dwordx4 v152, s[74:75]
	s_mov_b32 m0, s62
	s_nop 0
	global_load_lds_dwordx4 v146, s[100:101]
	s_mov_b32 m0, s63
	s_nop 0
	global_load_lds_dwordx4 v150, s[100:101]
	s_waitcnt vmcnt(8)
	s_waitcnt lgkmcnt(0)
	s_barrier
	s_setprio 1
	v_mfma_f32_16x16x32_bf16 v[62:65], v[130:133], v[194:197], v[62:65]
	v_mfma_f32_16x16x32_bf16 v[62:65], v[134:137], v[198:201], v[62:65]
	v_mfma_f32_16x16x32_bf16 v[58:61], v[138:141], v[194:197], v[58:61]
	v_mfma_f32_16x16x32_bf16 v[58:61], v[142:145], v[198:201], v[58:61]
	v_mfma_f32_16x16x32_bf16 v[54:57], v[166:169], v[194:197], v[54:57]
	v_mfma_f32_16x16x32_bf16 v[54:57], v[170:173], v[198:201], v[54:57]
	v_mfma_f32_16x16x32_bf16 v[50:53], v[186:189], v[194:197], v[50:53]
	v_mfma_f32_16x16x32_bf16 v[50:53], v[190:193], v[198:201], v[50:53]
	v_mfma_f32_16x16x32_bf16 v[46:49], v[130:133], v[202:205], v[46:49]
	v_mfma_f32_16x16x32_bf16 v[46:49], v[134:137], v[206:209], v[46:49]
	v_mfma_f32_16x16x32_bf16 v[42:45], v[138:141], v[202:205], v[42:45]
	v_mfma_f32_16x16x32_bf16 v[42:45], v[142:145], v[206:209], v[42:45]
	v_mfma_f32_16x16x32_bf16 v[38:41], v[166:169], v[202:205], v[38:41]
	v_mfma_f32_16x16x32_bf16 v[38:41], v[170:173], v[206:209], v[38:41]
	v_mfma_f32_16x16x32_bf16 v[34:37], v[186:189], v[202:205], v[34:37]
	v_mfma_f32_16x16x32_bf16 v[34:37], v[190:193], v[206:209], v[34:37]
	v_mfma_f32_16x16x32_bf16 v[30:33], v[130:133], v[210:213], v[30:33]
	v_mfma_f32_16x16x32_bf16 v[30:33], v[134:137], v[214:217], v[30:33]
	v_mfma_f32_16x16x32_bf16 v[26:29], v[138:141], v[210:213], v[26:29]
	v_mfma_f32_16x16x32_bf16 v[26:29], v[142:145], v[214:217], v[26:29]
	v_mfma_f32_16x16x32_bf16 v[22:25], v[166:169], v[210:213], v[22:25]
	v_mfma_f32_16x16x32_bf16 v[22:25], v[170:173], v[214:217], v[22:25]
	v_mfma_f32_16x16x32_bf16 v[18:21], v[186:189], v[210:213], v[18:21]
	v_mfma_f32_16x16x32_bf16 v[18:21], v[190:193], v[214:217], v[18:21]
	v_mfma_f32_16x16x32_bf16 v[14:17], v[130:133], v[218:221], v[14:17]
	v_mfma_f32_16x16x32_bf16 v[14:17], v[134:137], v[222:225], v[14:17]
	v_mfma_f32_16x16x32_bf16 v[10:13], v[138:141], v[218:221], v[10:13]
	v_mfma_f32_16x16x32_bf16 v[10:13], v[142:145], v[222:225], v[10:13]
	v_mfma_f32_16x16x32_bf16 v[6:9], v[166:169], v[218:221], v[6:9]
	v_mfma_f32_16x16x32_bf16 v[6:9], v[170:173], v[222:225], v[6:9]
	v_mfma_f32_16x16x32_bf16 v[2:5], v[186:189], v[218:221], v[2:5]
	v_mfma_f32_16x16x32_bf16 v[2:5], v[190:193], v[222:225], v[2:5]
	s_setprio 0
	s_barrier
	s_add_i32 s73, s73, 2
	s_add_u32 s50, s50, 0x100
	s_addc_u32 s51, s51, 0
	s_add_u32 s71, s71, 0x100
	s_addc_u32 s72, s72, 0
	s_cmp_gt_u32 s73, 61
	s_cbranch_scc0 .LBB0_2109
	s_and_b64 vcc, exec, s[40:41]
	s_cbranch_vccz .LBB0_2112
	s_barrier

.LBB0_2212:
	ds_read_b128 v[150:153], v162
	ds_read_b128 v[168:171], v162 offset:1024
	ds_read_b128 v[172:175], v162 offset:2048
	ds_read_b128 v[176:179], v162 offset:3072
	ds_read_b128 v[186:189], v163
	ds_read_b128 v[190:193], v163 offset:1024
	ds_read_b128 v[194:197], v163 offset:2048
	ds_read_b128 v[198:201], v163 offset:3072
	s_add_u32 s50, s6, 0xfff00080
	s_addc_u32 s51, s7, -1
	s_cmp_eq_u32 s79, 60
	s_cselect_b32 s81, s45, s51
	s_cselect_b32 s80, s75, s50
	s_cselect_b32 s51, s43, s78
	s_cselect_b32 s50, s76, s77
	s_add_i32 m0, s33, 0xc000
	ds_read_b128 v[202:205], v164
	ds_read_b128 v[206:209], v164 offset:1024
	ds_read_b128 v[210:213], v164 offset:2048
	ds_read_b128 v[214:217], v164 offset:3072
	ds_read_b128 v[218:221], v164 offset:4096
	ds_read_b128 v[222:225], v164 offset:5120
	ds_read_b128 v[226:229], v164 offset:6144
	ds_read_b128 v[230:233], v164 offset:7168
	global_load_lds_dwordx4 v142, s[6:7]
	s_add_i32 m0, s33, 0xe000
	s_nop 0
	global_load_lds_dwordx4 v144, s[6:7]
	s_waitcnt vmcnt(8)
	s_waitcnt lgkmcnt(0)
	s_barrier
	s_setprio 1
	v_mfma_f32_16x16x32_bf16 v[126:129], v[150:153], v[202:205], v[126:129]
	v_mfma_f32_16x16x32_bf16 v[126:129], v[168:171], v[206:209], v[126:129]
	v_mfma_f32_16x16x32_bf16 v[118:121], v[172:175], v[202:205], v[118:121]
	v_mfma_f32_16x16x32_bf16 v[118:121], v[176:179], v[206:209], v[118:121]
	v_mfma_f32_16x16x32_bf16 v[122:125], v[186:189], v[202:205], v[122:125]
	v_mfma_f32_16x16x32_bf16 v[122:125], v[190:193], v[206:209], v[122:125]
	v_mfma_f32_16x16x32_bf16 v[114:117], v[194:197], v[202:205], v[114:117]
	v_mfma_f32_16x16x32_bf16 v[114:117], v[198:201], v[206:209], v[114:117]
	v_mfma_f32_16x16x32_bf16 v[110:113], v[150:153], v[210:213], v[110:113]
	v_mfma_f32_16x16x32_bf16 v[110:113], v[168:171], v[214:217], v[110:113]
	v_mfma_f32_16x16x32_bf16 v[102:105], v[172:175], v[210:213], v[102:105]
	v_mfma_f32_16x16x32_bf16 v[102:105], v[176:179], v[214:217], v[102:105]
	v_mfma_f32_16x16x32_bf16 v[106:109], v[186:189], v[210:213], v[106:109]
	v_mfma_f32_16x16x32_bf16 v[106:109], v[190:193], v[214:217], v[106:109]
	v_mfma_f32_16x16x32_bf16 v[98:101], v[194:197], v[210:213], v[98:101]
	v_mfma_f32_16x16x32_bf16 v[98:101], v[198:201], v[214:217], v[98:101]
	v_mfma_f32_16x16x32_bf16 v[94:97], v[150:153], v[218:221], v[94:97]
	v_mfma_f32_16x16x32_bf16 v[94:97], v[168:171], v[222:225], v[94:97]
	v_mfma_f32_16x16x32_bf16 v[86:89], v[172:175], v[218:221], v[86:89]
	v_mfma_f32_16x16x32_bf16 v[86:89], v[176:179], v[222:225], v[86:89]
	v_mfma_f32_16x16x32_bf16 v[90:93], v[186:189], v[218:221], v[90:93]
	v_mfma_f32_16x16x32_bf16 v[90:93], v[190:193], v[222:225], v[90:93]
	v_mfma_f32_16x16x32_bf16 v[82:85], v[194:197], v[218:221], v[82:85]
	v_mfma_f32_16x16x32_bf16 v[82:85], v[198:201], v[222:225], v[82:85]
	v_mfma_f32_16x16x32_bf16 v[78:81], v[150:153], v[226:229], v[78:81]
	v_mfma_f32_16x16x32_bf16 v[78:81], v[168:171], v[230:233], v[78:81]
	v_mfma_f32_16x16x32_bf16 v[70:73], v[172:175], v[226:229], v[70:73]
	v_mfma_f32_16x16x32_bf16 v[70:73], v[176:179], v[230:233], v[70:73]
	v_mfma_f32_16x16x32_bf16 v[74:77], v[186:189], v[226:229], v[74:77]
	v_mfma_f32_16x16x32_bf16 v[74:77], v[190:193], v[230:233], v[74:77]
	v_mfma_f32_16x16x32_bf16 v[66:69], v[194:197], v[226:229], v[66:69]
	v_mfma_f32_16x16x32_bf16 v[66:69], v[198:201], v[230:233], v[66:69]
	s_setprio 0
	s_barrier
	s_add_i32 s82, s68, s29
	s_add_u32 s98, s50, 0x80
	s_addc_u32 s99, s51, 0
	s_mov_b32 m0, s82
	ds_read_b128 v[202:205], v164 offset:16384
	ds_read_b128 v[206:209], v164 offset:17408
	ds_read_b128 v[210:213], v164 offset:18432
	ds_read_b128 v[214:217], v164 offset:19456
	ds_read_b128 v[218:221], v164 offset:20480
	ds_read_b128 v[222:225], v164 offset:21504
	ds_read_b128 v[226:229], v164 offset:22528
	ds_read_b128 v[230:233], v164 offset:23552
	global_load_lds_dwordx4 v134, s[50:51]
	s_add_i32 m0, s82, 0x2000
	s_add_u32 s82, s50, 0x100000
	s_addc_u32 s83, s51, 0
	s_add_i32 s84, s69, s29
	global_load_lds_dwordx4 v138, s[50:51]
	s_mov_b32 m0, s84
	global_load_lds_dwordx4 v134, s[82:83]
	s_add_i32 m0, s84, 0x2000
	s_nop 0
	global_load_lds_dwordx4 v138, s[82:83]
	s_add_u32 s100, s80, 0x80
	s_addc_u32 s101, s81, 0
	s_mov_b32 m0, s33
	s_nop 0
	global_load_lds_dwordx4 v132, s[80:81]
	s_mov_b32 m0, s35
	s_nop 0
	global_load_lds_dwordx4 v136, s[80:81]
	s_waitcnt vmcnt(8)
	s_waitcnt lgkmcnt(0)
	s_barrier
	s_setprio 1
	v_mfma_f32_16x16x32_bf16 v[62:65], v[150:153], v[202:205], v[62:65]
	v_mfma_f32_16x16x32_bf16 v[62:65], v[168:171], v[206:209], v[62:65]
	v_mfma_f32_16x16x32_bf16 v[54:57], v[172:175], v[202:205], v[54:57]
	v_mfma_f32_16x16x32_bf16 v[54:57], v[176:179], v[206:209], v[54:57]
	v_mfma_f32_16x16x32_bf16 v[58:61], v[186:189], v[202:205], v[58:61]
	v_mfma_f32_16x16x32_bf16 v[58:61], v[190:193], v[206:209], v[58:61]
	v_mfma_f32_16x16x32_bf16 v[50:53], v[194:197], v[202:205], v[50:53]
	v_mfma_f32_16x16x32_bf16 v[50:53], v[198:201], v[206:209], v[50:53]
	v_mfma_f32_16x16x32_bf16 v[46:49], v[150:153], v[210:213], v[46:49]
	v_mfma_f32_16x16x32_bf16 v[46:49], v[168:171], v[214:217], v[46:49]
	v_mfma_f32_16x16x32_bf16 v[38:41], v[172:175], v[210:213], v[38:41]
	v_mfma_f32_16x16x32_bf16 v[38:41], v[176:179], v[214:217], v[38:41]
	v_mfma_f32_16x16x32_bf16 v[42:45], v[186:189], v[210:213], v[42:45]
	v_mfma_f32_16x16x32_bf16 v[42:45], v[190:193], v[214:217], v[42:45]
	v_mfma_f32_16x16x32_bf16 v[34:37], v[194:197], v[210:213], v[34:37]
	v_mfma_f32_16x16x32_bf16 v[34:37], v[198:201], v[214:217], v[34:37]
	v_mfma_f32_16x16x32_bf16 v[30:33], v[150:153], v[218:221], v[30:33]
	v_mfma_f32_16x16x32_bf16 v[30:33], v[168:171], v[222:225], v[30:33]
	v_mfma_f32_16x16x32_bf16 v[22:25], v[172:175], v[218:221], v[22:25]
	v_mfma_f32_16x16x32_bf16 v[22:25], v[176:179], v[222:225], v[22:25]
	v_mfma_f32_16x16x32_bf16 v[26:29], v[186:189], v[218:221], v[26:29]
	v_mfma_f32_16x16x32_bf16 v[26:29], v[190:193], v[222:225], v[26:29]
	v_mfma_f32_16x16x32_bf16 v[18:21], v[194:197], v[218:221], v[18:21]
	v_mfma_f32_16x16x32_bf16 v[18:21], v[198:201], v[222:225], v[18:21]
	v_mfma_f32_16x16x32_bf16 v[14:17], v[150:153], v[226:229], v[14:17]
	v_mfma_f32_16x16x32_bf16 v[14:17], v[168:171], v[230:233], v[14:17]
	v_mfma_f32_16x16x32_bf16 v[6:9], v[172:175], v[226:229], v[6:9]
	v_mfma_f32_16x16x32_bf16 v[6:9], v[176:179], v[230:233], v[6:9]
	v_mfma_f32_16x16x32_bf16 v[10:13], v[186:189], v[226:229], v[10:13]
	v_mfma_f32_16x16x32_bf16 v[10:13], v[190:193], v[230:233], v[10:13]
	v_mfma_f32_16x16x32_bf16 v[2:5], v[194:197], v[226:229], v[2:5]
	v_mfma_f32_16x16x32_bf16 v[2:5], v[198:201], v[230:233], v[2:5]
	s_setprio 0
	s_barrier
	s_add_i32 s82, 0, 0x18000
	v_add_u32_e32 v140, s82, v158
	s_add_i32 s83, 0, 0x1c000
	ds_read_b128 v[150:153], v140
	ds_read_b128 v[168:171], v140 offset:1024
	ds_read_b128 v[172:175], v140 offset:2048
	ds_read_b128 v[176:179], v140 offset:3072
	v_add_u32_e32 v140, s83, v158
	ds_read_b128 v[186:189], v140
	ds_read_b128 v[190:193], v140 offset:1024
	ds_read_b128 v[194:197], v140 offset:2048
	ds_read_b128 v[198:201], v140 offset:3072
	s_add_u32 s80, s80, 0x100000
	s_addc_u32 s81, s81, 0
	s_mov_b32 m0, s59
	ds_read_b128 v[202:205], v164 offset:32768
	ds_read_b128 v[206:209], v164 offset:33792
	ds_read_b128 v[210:213], v164 offset:34816
	ds_read_b128 v[214:217], v164 offset:35840
	ds_read_b128 v[218:221], v164 offset:36864
	ds_read_b128 v[222:225], v164 offset:37888
	ds_read_b128 v[226:229], v164 offset:38912
	ds_read_b128 v[230:233], v164 offset:39936
	global_load_lds_dwordx4 v132, s[80:81]
	s_mov_b32 m0, s62
	s_nop 0
	global_load_lds_dwordx4 v136, s[80:81]
	s_waitcnt vmcnt(8)
	s_waitcnt lgkmcnt(0)
	s_barrier
	s_setprio 1
	v_mfma_f32_16x16x32_bf16 v[126:129], v[150:153], v[202:205], v[126:129]
	v_mfma_f32_16x16x32_bf16 v[126:129], v[168:171], v[206:209], v[126:129]
	v_mfma_f32_16x16x32_bf16 v[118:121], v[172:175], v[202:205], v[118:121]
	v_mfma_f32_16x16x32_bf16 v[118:121], v[176:179], v[206:209], v[118:121]
	v_mfma_f32_16x16x32_bf16 v[122:125], v[186:189], v[202:205], v[122:125]
	v_mfma_f32_16x16x32_bf16 v[122:125], v[190:193], v[206:209], v[122:125]
	v_mfma_f32_16x16x32_bf16 v[114:117], v[194:197], v[202:205], v[114:117]
	v_mfma_f32_16x16x32_bf16 v[114:117], v[198:201], v[206:209], v[114:117]
	v_mfma_f32_16x16x32_bf16 v[110:113], v[150:153], v[210:213], v[110:113]
	v_mfma_f32_16x16x32_bf16 v[110:113], v[168:171], v[214:217], v[110:113]
	v_mfma_f32_16x16x32_bf16 v[102:105], v[172:175], v[210:213], v[102:105]
	v_mfma_f32_16x16x32_bf16 v[102:105], v[176:179], v[214:217], v[102:105]
	v_mfma_f32_16x16x32_bf16 v[106:109], v[186:189], v[210:213], v[106:109]
	v_mfma_f32_16x16x32_bf16 v[106:109], v[190:193], v[214:217], v[106:109]
	v_mfma_f32_16x16x32_bf16 v[98:101], v[194:197], v[210:213], v[98:101]
	v_mfma_f32_16x16x32_bf16 v[98:101], v[198:201], v[214:217], v[98:101]
	v_mfma_f32_16x16x32_bf16 v[94:97], v[150:153], v[218:221], v[94:97]
	v_mfma_f32_16x16x32_bf16 v[94:97], v[168:171], v[222:225], v[94:97]
	v_mfma_f32_16x16x32_bf16 v[86:89], v[172:175], v[218:221], v[86:89]
	v_mfma_f32_16x16x32_bf16 v[86:89], v[176:179], v[222:225], v[86:89]
	v_mfma_f32_16x16x32_bf16 v[90:93], v[186:189], v[218:221], v[90:93]
	v_mfma_f32_16x16x32_bf16 v[90:93], v[190:193], v[222:225], v[90:93]
	v_mfma_f32_16x16x32_bf16 v[82:85], v[194:197], v[218:221], v[82:85]
	v_mfma_f32_16x16x32_bf16 v[82:85], v[198:201], v[222:225], v[82:85]
	v_mfma_f32_16x16x32_bf16 v[78:81], v[150:153], v[226:229], v[78:81]
	v_mfma_f32_16x16x32_bf16 v[78:81], v[168:171], v[230:233], v[78:81]
	v_mfma_f32_16x16x32_bf16 v[70:73], v[172:175], v[226:229], v[70:73]
	v_mfma_f32_16x16x32_bf16 v[70:73], v[176:179], v[230:233], v[70:73]
	v_mfma_f32_16x16x32_bf16 v[74:77], v[186:189], v[226:229], v[74:77]
	v_mfma_f32_16x16x32_bf16 v[74:77], v[190:193], v[230:233], v[74:77]
	v_mfma_f32_16x16x32_bf16 v[66:69], v[194:197], v[226:229], v[66:69]
	v_mfma_f32_16x16x32_bf16 v[66:69], v[198:201], v[230:233], v[66:69]
	s_setprio 0
	s_barrier
	s_add_i32 s80, s82, s29
	s_mov_b32 m0, s80
	ds_read_b128 v[202:205], v164 offset:49152
	ds_read_b128 v[206:209], v164 offset:50176
	ds_read_b128 v[210:213], v164 offset:51200
	ds_read_b128 v[214:217], v164 offset:52224
	ds_read_b128 v[218:221], v164 offset:53248
	ds_read_b128 v[222:225], v164 offset:54272
	ds_read_b128 v[226:229], v164 offset:55296
	ds_read_b128 v[230:233], v164 offset:56320
	global_load_lds_dwordx4 v134, s[98:99]
	s_add_i32 m0, s80, 0x2000
	s_add_u32 s50, s50, 0x100080
	s_addc_u32 s51, s51, 0
	s_add_i32 s80, s83, s29
	global_load_lds_dwordx4 v138, s[98:99]
	s_mov_b32 m0, s80
	s_nop 0
	global_load_lds_dwordx4 v134, s[50:51]
	s_add_i32 m0, s80, 0x2000
	s_nop 0
	global_load_lds_dwordx4 v138, s[50:51]
	s_mov_b32 m0, s65
	s_nop 0
	global_load_lds_dwordx4 v132, s[100:101]
	s_mov_b32 m0, s66
	s_nop 0
	global_load_lds_dwordx4 v136, s[100:101]
	s_waitcnt vmcnt(8)
	s_waitcnt lgkmcnt(0)
	s_barrier
	s_setprio 1
	v_mfma_f32_16x16x32_bf16 v[62:65], v[150:153], v[202:205], v[62:65]
	v_mfma_f32_16x16x32_bf16 v[62:65], v[168:171], v[206:209], v[62:65]
	v_mfma_f32_16x16x32_bf16 v[54:57], v[172:175], v[202:205], v[54:57]
	v_mfma_f32_16x16x32_bf16 v[54:57], v[176:179], v[206:209], v[54:57]
	v_mfma_f32_16x16x32_bf16 v[58:61], v[186:189], v[202:205], v[58:61]
	v_mfma_f32_16x16x32_bf16 v[58:61], v[190:193], v[206:209], v[58:61]
	v_mfma_f32_16x16x32_bf16 v[50:53], v[194:197], v[202:205], v[50:53]
	v_mfma_f32_16x16x32_bf16 v[50:53], v[198:201], v[206:209], v[50:53]
	v_mfma_f32_16x16x32_bf16 v[46:49], v[150:153], v[210:213], v[46:49]
	v_mfma_f32_16x16x32_bf16 v[46:49], v[168:171], v[214:217], v[46:49]
	v_mfma_f32_16x16x32_bf16 v[38:41], v[172:175], v[210:213], v[38:41]
	v_mfma_f32_16x16x32_bf16 v[38:41], v[176:179], v[214:217], v[38:41]
	v_mfma_f32_16x16x32_bf16 v[42:45], v[186:189], v[210:213], v[42:45]
	v_mfma_f32_16x16x32_bf16 v[42:45], v[190:193], v[214:217], v[42:45]
	v_mfma_f32_16x16x32_bf16 v[34:37], v[194:197], v[210:213], v[34:37]
	v_mfma_f32_16x16x32_bf16 v[34:37], v[198:201], v[214:217], v[34:37]
	v_mfma_f32_16x16x32_bf16 v[30:33], v[150:153], v[218:221], v[30:33]
	v_mfma_f32_16x16x32_bf16 v[30:33], v[168:171], v[222:225], v[30:33]
	v_mfma_f32_16x16x32_bf16 v[22:25], v[172:175], v[218:221], v[22:25]
	v_mfma_f32_16x16x32_bf16 v[22:25], v[176:179], v[222:225], v[22:25]
	v_mfma_f32_16x16x32_bf16 v[26:29], v[186:189], v[218:221], v[26:29]
	v_mfma_f32_16x16x32_bf16 v[26:29], v[190:193], v[222:225], v[26:29]
	v_mfma_f32_16x16x32_bf16 v[18:21], v[194:197], v[218:221], v[18:21]
	v_mfma_f32_16x16x32_bf16 v[18:21], v[198:201], v[222:225], v[18:21]
	v_mfma_f32_16x16x32_bf16 v[14:17], v[150:153], v[226:229], v[14:17]
	v_mfma_f32_16x16x32_bf16 v[14:17], v[168:171], v[230:233], v[14:17]
	v_mfma_f32_16x16x32_bf16 v[6:9], v[172:175], v[226:229], v[6:9]
	v_mfma_f32_16x16x32_bf16 v[6:9], v[176:179], v[230:233], v[6:9]
	v_mfma_f32_16x16x32_bf16 v[10:13], v[186:189], v[226:229], v[10:13]
	v_mfma_f32_16x16x32_bf16 v[10:13], v[190:193], v[230:233], v[10:13]
	v_mfma_f32_16x16x32_bf16 v[2:5], v[194:197], v[226:229], v[2:5]
	v_mfma_f32_16x16x32_bf16 v[2:5], v[198:201], v[230:233], v[2:5]
	s_setprio 0
	s_barrier
	s_add_i32 s79, s79, 2
	s_add_u32 s6, s6, 0x100
	s_addc_u32 s7, s7, 0
	s_add_u32 s77, s77, 0x100
	s_addc_u32 s78, s78, 0
	s_cmp_gt_u32 s79, 61
	s_cbranch_scc0 .LBB0_2212
	s_and_b64 vcc, exec, s[40:41]
	s_cbranch_vccz .LBB0_2215
	s_barrier

.LBB0_2340:
	ds_read_b128 v[130:133], v163
	ds_read_b128 v[134:137], v163 offset:1024
	ds_read_b128 v[138:141], v163 offset:2048
	ds_read_b128 v[142:145], v163 offset:3072
	ds_read_b128 v[146:149], v190
	ds_read_b128 v[150:153], v190 offset:1024
	ds_read_b128 v[174:177], v190 offset:2048
	ds_read_b128 v[178:181], v190 offset:3072
	s_add_u32 s42, s40, 0xffd50080
	s_addc_u32 s43, s41, -1
	s_cmpk_eq_i32 s71, 0xa8
	s_cselect_b32 s45, s1, s43
	s_cselect_b32 s44, s0, s42
	s_cselect_b32 s43, s39, s70
	s_cselect_b32 s42, s38, s12
	s_add_i32 m0, s46, 0xc000
	ds_read_b128 v[186:189], v191
	ds_read_b128 v[194:197], v191 offset:1024
	ds_read_b128 v[198:201], v191 offset:2048
	ds_read_b128 v[202:205], v191 offset:3072
	ds_read_b128 v[206:209], v191 offset:4096
	ds_read_b128 v[210:213], v191 offset:5120
	ds_read_b128 v[214:217], v191 offset:6144
	ds_read_b128 v[218:221], v191 offset:7168
	global_load_lds_dwordx4 v166, s[40:41]
	s_add_i32 m0, s46, 0xe000
	s_nop 0
	global_load_lds_dwordx4 v168, s[40:41]
	s_waitcnt vmcnt(8)
	s_waitcnt lgkmcnt(0)
	s_barrier
	s_setprio 1
	v_mfma_f32_16x16x32_bf16 v[126:129], v[130:133], v[186:189], v[126:129]
	v_mfma_f32_16x16x32_bf16 v[126:129], v[134:137], v[194:197], v[126:129]
	v_mfma_f32_16x16x32_bf16 v[122:125], v[138:141], v[186:189], v[122:125]
	v_mfma_f32_16x16x32_bf16 v[122:125], v[142:145], v[194:197], v[122:125]
	v_mfma_f32_16x16x32_bf16 v[118:121], v[146:149], v[186:189], v[118:121]
	v_mfma_f32_16x16x32_bf16 v[118:121], v[150:153], v[194:197], v[118:121]
	v_mfma_f32_16x16x32_bf16 v[114:117], v[174:177], v[186:189], v[114:117]
	v_mfma_f32_16x16x32_bf16 v[114:117], v[178:181], v[194:197], v[114:117]
	v_mfma_f32_16x16x32_bf16 v[110:113], v[130:133], v[198:201], v[110:113]
	v_mfma_f32_16x16x32_bf16 v[110:113], v[134:137], v[202:205], v[110:113]
	v_mfma_f32_16x16x32_bf16 v[106:109], v[138:141], v[198:201], v[106:109]
	v_mfma_f32_16x16x32_bf16 v[106:109], v[142:145], v[202:205], v[106:109]
	v_mfma_f32_16x16x32_bf16 v[102:105], v[146:149], v[198:201], v[102:105]
	v_mfma_f32_16x16x32_bf16 v[102:105], v[150:153], v[202:205], v[102:105]
	v_mfma_f32_16x16x32_bf16 v[98:101], v[174:177], v[198:201], v[98:101]
	v_mfma_f32_16x16x32_bf16 v[98:101], v[178:181], v[202:205], v[98:101]
	v_mfma_f32_16x16x32_bf16 v[94:97], v[130:133], v[206:209], v[94:97]
	v_mfma_f32_16x16x32_bf16 v[94:97], v[134:137], v[210:213], v[94:97]
	v_mfma_f32_16x16x32_bf16 v[90:93], v[138:141], v[206:209], v[90:93]
	v_mfma_f32_16x16x32_bf16 v[90:93], v[142:145], v[210:213], v[90:93]
	v_mfma_f32_16x16x32_bf16 v[86:89], v[146:149], v[206:209], v[86:89]
	v_mfma_f32_16x16x32_bf16 v[86:89], v[150:153], v[210:213], v[86:89]
	v_mfma_f32_16x16x32_bf16 v[82:85], v[174:177], v[206:209], v[82:85]
	v_mfma_f32_16x16x32_bf16 v[82:85], v[178:181], v[210:213], v[82:85]
	v_mfma_f32_16x16x32_bf16 v[78:81], v[130:133], v[214:217], v[78:81]
	v_mfma_f32_16x16x32_bf16 v[78:81], v[134:137], v[218:221], v[78:81]
	v_mfma_f32_16x16x32_bf16 v[74:77], v[138:141], v[214:217], v[74:77]
	v_mfma_f32_16x16x32_bf16 v[74:77], v[142:145], v[218:221], v[74:77]
	v_mfma_f32_16x16x32_bf16 v[70:73], v[146:149], v[214:217], v[70:73]
	v_mfma_f32_16x16x32_bf16 v[70:73], v[150:153], v[218:221], v[70:73]
	v_mfma_f32_16x16x32_bf16 v[66:69], v[174:177], v[214:217], v[66:69]
	v_mfma_f32_16x16x32_bf16 v[66:69], v[178:181], v[218:221], v[66:69]
	s_setprio 0
	s_barrier
	s_add_i32 s72, s65, s35
	s_add_u32 s98, s42, 0x80
	s_addc_u32 s99, s43, 0
	s_mov_b32 m0, s72
	ds_read_b128 v[186:189], v191 offset:16384
	ds_read_b128 v[194:197], v191 offset:17408
	ds_read_b128 v[198:201], v191 offset:18432
	ds_read_b128 v[202:205], v191 offset:19456
	ds_read_b128 v[206:209], v191 offset:20480
	ds_read_b128 v[210:213], v191 offset:21504
	ds_read_b128 v[214:217], v191 offset:22528
	ds_read_b128 v[218:221], v191 offset:23552
	global_load_lds_dwordx4 v156, s[42:43]
	s_add_i32 m0, s72, 0x2000
	s_add_u32 s72, s42, 0x2b0000
	s_addc_u32 s73, s43, 0
	s_add_i32 s74, s66, s35
	global_load_lds_dwordx4 v160, s[42:43]
	s_mov_b32 m0, s74
	global_load_lds_dwordx4 v156, s[72:73]
	s_add_i32 m0, s74, 0x2000
	s_nop 0
	global_load_lds_dwordx4 v160, s[72:73]
	s_add_u32 s100, s44, 0x80
	s_addc_u32 s101, s45, 0
	s_mov_b32 m0, s46
	s_nop 0
	global_load_lds_dwordx4 v154, s[44:45]
	s_mov_b32 m0, s47
	s_nop 0
	global_load_lds_dwordx4 v158, s[44:45]
	s_waitcnt vmcnt(8)
	s_waitcnt lgkmcnt(0)
	s_barrier
	s_setprio 1
	v_mfma_f32_16x16x32_bf16 v[62:65], v[130:133], v[186:189], v[62:65]
	v_mfma_f32_16x16x32_bf16 v[62:65], v[134:137], v[194:197], v[62:65]
	v_mfma_f32_16x16x32_bf16 v[58:61], v[138:141], v[186:189], v[58:61]
	v_mfma_f32_16x16x32_bf16 v[58:61], v[142:145], v[194:197], v[58:61]
	v_mfma_f32_16x16x32_bf16 v[54:57], v[146:149], v[186:189], v[54:57]
	v_mfma_f32_16x16x32_bf16 v[54:57], v[150:153], v[194:197], v[54:57]
	v_mfma_f32_16x16x32_bf16 v[50:53], v[174:177], v[186:189], v[50:53]
	v_mfma_f32_16x16x32_bf16 v[50:53], v[178:181], v[194:197], v[50:53]
	v_mfma_f32_16x16x32_bf16 v[46:49], v[130:133], v[198:201], v[46:49]
	v_mfma_f32_16x16x32_bf16 v[46:49], v[134:137], v[202:205], v[46:49]
	v_mfma_f32_16x16x32_bf16 v[42:45], v[138:141], v[198:201], v[42:45]
	v_mfma_f32_16x16x32_bf16 v[42:45], v[142:145], v[202:205], v[42:45]
	v_mfma_f32_16x16x32_bf16 v[38:41], v[146:149], v[198:201], v[38:41]
	v_mfma_f32_16x16x32_bf16 v[38:41], v[150:153], v[202:205], v[38:41]
	v_mfma_f32_16x16x32_bf16 v[34:37], v[174:177], v[198:201], v[34:37]
	v_mfma_f32_16x16x32_bf16 v[34:37], v[178:181], v[202:205], v[34:37]
	v_mfma_f32_16x16x32_bf16 v[30:33], v[130:133], v[206:209], v[30:33]
	v_mfma_f32_16x16x32_bf16 v[30:33], v[134:137], v[210:213], v[30:33]
	v_mfma_f32_16x16x32_bf16 v[26:29], v[138:141], v[206:209], v[26:29]
	v_mfma_f32_16x16x32_bf16 v[26:29], v[142:145], v[210:213], v[26:29]
	v_mfma_f32_16x16x32_bf16 v[22:25], v[146:149], v[206:209], v[22:25]
	v_mfma_f32_16x16x32_bf16 v[22:25], v[150:153], v[210:213], v[22:25]
	v_mfma_f32_16x16x32_bf16 v[18:21], v[174:177], v[206:209], v[18:21]
	v_mfma_f32_16x16x32_bf16 v[18:21], v[178:181], v[210:213], v[18:21]
	v_mfma_f32_16x16x32_bf16 v[14:17], v[130:133], v[214:217], v[14:17]
	v_mfma_f32_16x16x32_bf16 v[14:17], v[134:137], v[218:221], v[14:17]
	v_mfma_f32_16x16x32_bf16 v[10:13], v[138:141], v[214:217], v[10:13]
	v_mfma_f32_16x16x32_bf16 v[10:13], v[142:145], v[218:221], v[10:13]
	v_mfma_f32_16x16x32_bf16 v[6:9], v[146:149], v[214:217], v[6:9]
	v_mfma_f32_16x16x32_bf16 v[6:9], v[150:153], v[218:221], v[6:9]
	v_mfma_f32_16x16x32_bf16 v[2:5], v[174:177], v[214:217], v[2:5]
	v_mfma_f32_16x16x32_bf16 v[2:5], v[178:181], v[218:221], v[2:5]
	s_setprio 0
	s_barrier
	s_add_i32 s72, 0, 0x18000
	s_add_i32 s73, 0, 0x1c000
	v_add_u32_e32 v142, s72, v183
	v_add_u32_e32 v178, s73, v183
	ds_read_b128 v[130:133], v142
	ds_read_b128 v[134:137], v142 offset:1024
	ds_read_b128 v[138:141], v142 offset:2048
	ds_read_b128 v[142:145], v142 offset:3072
	ds_read_b128 v[146:149], v178
	ds_read_b128 v[150:153], v178 offset:1024
	ds_read_b128 v[174:177], v178 offset:2048
	ds_read_b128 v[178:181], v178 offset:3072
	s_add_u32 s44, s44, 0x2b0000
	s_addc_u32 s45, s45, 0
	s_mov_b32 m0, s48
	ds_read_b128 v[186:189], v191 offset:32768
	ds_read_b128 v[194:197], v191 offset:33792
	ds_read_b128 v[198:201], v191 offset:34816
	ds_read_b128 v[202:205], v191 offset:35840
	ds_read_b128 v[206:209], v191 offset:36864
	ds_read_b128 v[210:213], v191 offset:37888
	ds_read_b128 v[214:217], v191 offset:38912
	ds_read_b128 v[218:221], v191 offset:39936
	global_load_lds_dwordx4 v154, s[44:45]
	s_mov_b32 m0, s49
	s_nop 0
	global_load_lds_dwordx4 v158, s[44:45]
	s_waitcnt vmcnt(8)
	s_waitcnt lgkmcnt(0)
	s_barrier
	s_setprio 1
	v_mfma_f32_16x16x32_bf16 v[126:129], v[130:133], v[186:189], v[126:129]
	v_mfma_f32_16x16x32_bf16 v[126:129], v[134:137], v[194:197], v[126:129]
	v_mfma_f32_16x16x32_bf16 v[122:125], v[138:141], v[186:189], v[122:125]
	v_mfma_f32_16x16x32_bf16 v[122:125], v[142:145], v[194:197], v[122:125]
	v_mfma_f32_16x16x32_bf16 v[118:121], v[146:149], v[186:189], v[118:121]
	v_mfma_f32_16x16x32_bf16 v[118:121], v[150:153], v[194:197], v[118:121]
	v_mfma_f32_16x16x32_bf16 v[114:117], v[174:177], v[186:189], v[114:117]
	v_mfma_f32_16x16x32_bf16 v[114:117], v[178:181], v[194:197], v[114:117]
	v_mfma_f32_16x16x32_bf16 v[110:113], v[130:133], v[198:201], v[110:113]
	v_mfma_f32_16x16x32_bf16 v[110:113], v[134:137], v[202:205], v[110:113]
	v_mfma_f32_16x16x32_bf16 v[106:109], v[138:141], v[198:201], v[106:109]
	v_mfma_f32_16x16x32_bf16 v[106:109], v[142:145], v[202:205], v[106:109]
	v_mfma_f32_16x16x32_bf16 v[102:105], v[146:149], v[198:201], v[102:105]
	v_mfma_f32_16x16x32_bf16 v[102:105], v[150:153], v[202:205], v[102:105]
	v_mfma_f32_16x16x32_bf16 v[98:101], v[174:177], v[198:201], v[98:101]
	v_mfma_f32_16x16x32_bf16 v[98:101], v[178:181], v[202:205], v[98:101]
	v_mfma_f32_16x16x32_bf16 v[94:97], v[130:133], v[206:209], v[94:97]
	v_mfma_f32_16x16x32_bf16 v[94:97], v[134:137], v[210:213], v[94:97]
	v_mfma_f32_16x16x32_bf16 v[90:93], v[138:141], v[206:209], v[90:93]
	v_mfma_f32_16x16x32_bf16 v[90:93], v[142:145], v[210:213], v[90:93]
	v_mfma_f32_16x16x32_bf16 v[86:89], v[146:149], v[206:209], v[86:89]
	v_mfma_f32_16x16x32_bf16 v[86:89], v[150:153], v[210:213], v[86:89]
	v_mfma_f32_16x16x32_bf16 v[82:85], v[174:177], v[206:209], v[82:85]
	v_mfma_f32_16x16x32_bf16 v[82:85], v[178:181], v[210:213], v[82:85]
	v_mfma_f32_16x16x32_bf16 v[78:81], v[130:133], v[214:217], v[78:81]
	v_mfma_f32_16x16x32_bf16 v[78:81], v[134:137], v[218:221], v[78:81]
	v_mfma_f32_16x16x32_bf16 v[74:77], v[138:141], v[214:217], v[74:77]
	v_mfma_f32_16x16x32_bf16 v[74:77], v[142:145], v[218:221], v[74:77]
	v_mfma_f32_16x16x32_bf16 v[70:73], v[146:149], v[214:217], v[70:73]
	v_mfma_f32_16x16x32_bf16 v[70:73], v[150:153], v[218:221], v[70:73]
	v_mfma_f32_16x16x32_bf16 v[66:69], v[174:177], v[214:217], v[66:69]
	v_mfma_f32_16x16x32_bf16 v[66:69], v[178:181], v[218:221], v[66:69]
	s_setprio 0
	s_barrier
	s_add_i32 s44, s72, s35
	s_mov_b32 m0, s44
	ds_read_b128 v[186:189], v191 offset:49152
	ds_read_b128 v[194:197], v191 offset:50176
	ds_read_b128 v[198:201], v191 offset:51200
	ds_read_b128 v[202:205], v191 offset:52224
	ds_read_b128 v[206:209], v191 offset:53248
	ds_read_b128 v[210:213], v191 offset:54272
	ds_read_b128 v[214:217], v191 offset:55296
	ds_read_b128 v[218:221], v191 offset:56320
	global_load_lds_dwordx4 v156, s[98:99]
	s_add_i32 m0, s44, 0x2000
	s_add_u32 s42, s42, 0x2b0080
	s_addc_u32 s43, s43, 0
	s_add_i32 s44, s73, s35
	global_load_lds_dwordx4 v160, s[98:99]
	s_mov_b32 m0, s44
	s_nop 0
	global_load_lds_dwordx4 v156, s[42:43]
	s_add_i32 m0, s44, 0x2000
	s_nop 0
	global_load_lds_dwordx4 v160, s[42:43]
	s_mov_b32 m0, s51
	s_nop 0
	global_load_lds_dwordx4 v154, s[100:101]
	s_mov_b32 m0, s59
	s_nop 0
	global_load_lds_dwordx4 v158, s[100:101]
	s_waitcnt vmcnt(8)
	s_waitcnt lgkmcnt(0)
	s_barrier
	s_setprio 1
	v_mfma_f32_16x16x32_bf16 v[62:65], v[130:133], v[186:189], v[62:65]
	v_mfma_f32_16x16x32_bf16 v[62:65], v[134:137], v[194:197], v[62:65]
	v_mfma_f32_16x16x32_bf16 v[58:61], v[138:141], v[186:189], v[58:61]
	v_mfma_f32_16x16x32_bf16 v[58:61], v[142:145], v[194:197], v[58:61]
	v_mfma_f32_16x16x32_bf16 v[54:57], v[146:149], v[186:189], v[54:57]
	v_mfma_f32_16x16x32_bf16 v[54:57], v[150:153], v[194:197], v[54:57]
	v_mfma_f32_16x16x32_bf16 v[50:53], v[174:177], v[186:189], v[50:53]
	v_mfma_f32_16x16x32_bf16 v[50:53], v[178:181], v[194:197], v[50:53]
	v_mfma_f32_16x16x32_bf16 v[46:49], v[130:133], v[198:201], v[46:49]
	v_mfma_f32_16x16x32_bf16 v[46:49], v[134:137], v[202:205], v[46:49]
	v_mfma_f32_16x16x32_bf16 v[42:45], v[138:141], v[198:201], v[42:45]
	v_mfma_f32_16x16x32_bf16 v[42:45], v[142:145], v[202:205], v[42:45]
	v_mfma_f32_16x16x32_bf16 v[38:41], v[146:149], v[198:201], v[38:41]
	v_mfma_f32_16x16x32_bf16 v[38:41], v[150:153], v[202:205], v[38:41]
	v_mfma_f32_16x16x32_bf16 v[34:37], v[174:177], v[198:201], v[34:37]
	v_mfma_f32_16x16x32_bf16 v[34:37], v[178:181], v[202:205], v[34:37]
	v_mfma_f32_16x16x32_bf16 v[30:33], v[130:133], v[206:209], v[30:33]
	v_mfma_f32_16x16x32_bf16 v[30:33], v[134:137], v[210:213], v[30:33]
	v_mfma_f32_16x16x32_bf16 v[26:29], v[138:141], v[206:209], v[26:29]
	v_mfma_f32_16x16x32_bf16 v[26:29], v[142:145], v[210:213], v[26:29]
	v_mfma_f32_16x16x32_bf16 v[22:25], v[146:149], v[206:209], v[22:25]
	v_mfma_f32_16x16x32_bf16 v[22:25], v[150:153], v[210:213], v[22:25]
	v_mfma_f32_16x16x32_bf16 v[18:21], v[174:177], v[206:209], v[18:21]
	v_mfma_f32_16x16x32_bf16 v[18:21], v[178:181], v[210:213], v[18:21]
	v_mfma_f32_16x16x32_bf16 v[14:17], v[130:133], v[214:217], v[14:17]
	v_mfma_f32_16x16x32_bf16 v[14:17], v[134:137], v[218:221], v[14:17]
	v_mfma_f32_16x16x32_bf16 v[10:13], v[138:141], v[214:217], v[10:13]
	v_mfma_f32_16x16x32_bf16 v[10:13], v[142:145], v[218:221], v[10:13]
	v_mfma_f32_16x16x32_bf16 v[6:9], v[146:149], v[214:217], v[6:9]
	v_mfma_f32_16x16x32_bf16 v[6:9], v[150:153], v[218:221], v[6:9]
	v_mfma_f32_16x16x32_bf16 v[2:5], v[174:177], v[214:217], v[2:5]
	v_mfma_f32_16x16x32_bf16 v[2:5], v[178:181], v[218:221], v[2:5]
	s_setprio 0
	s_barrier
	s_add_i32 s71, s71, 2
	s_add_u32 s40, s40, 0x100
	s_addc_u32 s41, s41, 0
	s_add_u32 s12, s12, 0x100
	s_addc_u32 s70, s70, 0
	s_cmpk_gt_u32 s71, 0xa9
	s_cbranch_scc0 .LBB0_2340
	s_and_b64 vcc, exec, s[36:37]
	s_cbranch_vccz .LBB0_2343
	s_barrier

.LBB0_2464:
	ds_read_b128 v[150:153], v167
	ds_read_b128 v[172:175], v167 offset:1024
	ds_read_b128 v[176:179], v167 offset:2048
	ds_read_b128 v[184:187], v167 offset:3072
	ds_read_b128 v[188:191], v168
	ds_read_b128 v[192:195], v168 offset:1024
	ds_read_b128 v[196:199], v168 offset:2048
	ds_read_b128 v[200:203], v168 offset:3072
	s_add_u32 s74, s6, 0xfff00080
	s_addc_u32 s75, s7, -1
	s_cmp_eq_u32 s87, 60
	s_cselect_b32 s77, s47, s75
	s_cselect_b32 s76, s83, s74
	s_cselect_b32 s75, s45, s86
	s_cselect_b32 s74, s84, s85
	s_add_i32 m0, s59, 0xc000
	ds_read_b128 v[204:207], v169
	ds_read_b128 v[208:211], v169 offset:1024
	ds_read_b128 v[212:215], v169 offset:2048
	ds_read_b128 v[216:219], v169 offset:3072
	ds_read_b128 v[220:223], v169 offset:4096
	ds_read_b128 v[224:227], v169 offset:5120
	ds_read_b128 v[228:231], v169 offset:6144
	ds_read_b128 v[232:235], v169 offset:7168
	global_load_lds_dwordx4 v142, s[6:7]
	s_add_i32 m0, s59, 0xe000
	s_nop 0
	global_load_lds_dwordx4 v144, s[6:7]
	s_waitcnt vmcnt(8)
	s_waitcnt lgkmcnt(0)
	s_barrier
	s_setprio 1
	v_mfma_f32_16x16x32_bf16 v[126:129], v[150:153], v[204:207], v[126:129]
	v_mfma_f32_16x16x32_bf16 v[126:129], v[172:175], v[208:211], v[126:129]
	v_mfma_f32_16x16x32_bf16 v[122:125], v[176:179], v[204:207], v[122:125]
	v_mfma_f32_16x16x32_bf16 v[122:125], v[184:187], v[208:211], v[122:125]
	v_mfma_f32_16x16x32_bf16 v[118:121], v[188:191], v[204:207], v[118:121]
	v_mfma_f32_16x16x32_bf16 v[118:121], v[192:195], v[208:211], v[118:121]
	v_mfma_f32_16x16x32_bf16 v[114:117], v[196:199], v[204:207], v[114:117]
	v_mfma_f32_16x16x32_bf16 v[114:117], v[200:203], v[208:211], v[114:117]
	v_mfma_f32_16x16x32_bf16 v[110:113], v[150:153], v[212:215], v[110:113]
	v_mfma_f32_16x16x32_bf16 v[110:113], v[172:175], v[216:219], v[110:113]
	v_mfma_f32_16x16x32_bf16 v[106:109], v[176:179], v[212:215], v[106:109]
	v_mfma_f32_16x16x32_bf16 v[106:109], v[184:187], v[216:219], v[106:109]
	v_mfma_f32_16x16x32_bf16 v[102:105], v[188:191], v[212:215], v[102:105]
	v_mfma_f32_16x16x32_bf16 v[102:105], v[192:195], v[216:219], v[102:105]
	v_mfma_f32_16x16x32_bf16 v[98:101], v[196:199], v[212:215], v[98:101]
	v_mfma_f32_16x16x32_bf16 v[98:101], v[200:203], v[216:219], v[98:101]
	v_mfma_f32_16x16x32_bf16 v[94:97], v[150:153], v[220:223], v[94:97]
	v_mfma_f32_16x16x32_bf16 v[94:97], v[172:175], v[224:227], v[94:97]
	v_mfma_f32_16x16x32_bf16 v[90:93], v[176:179], v[220:223], v[90:93]
	v_mfma_f32_16x16x32_bf16 v[90:93], v[184:187], v[224:227], v[90:93]
	v_mfma_f32_16x16x32_bf16 v[86:89], v[188:191], v[220:223], v[86:89]
	v_mfma_f32_16x16x32_bf16 v[86:89], v[192:195], v[224:227], v[86:89]
	v_mfma_f32_16x16x32_bf16 v[82:85], v[196:199], v[220:223], v[82:85]
	v_mfma_f32_16x16x32_bf16 v[82:85], v[200:203], v[224:227], v[82:85]
	v_mfma_f32_16x16x32_bf16 v[78:81], v[150:153], v[228:231], v[78:81]
	v_mfma_f32_16x16x32_bf16 v[78:81], v[172:175], v[232:235], v[78:81]
	v_mfma_f32_16x16x32_bf16 v[74:77], v[176:179], v[228:231], v[74:77]
	v_mfma_f32_16x16x32_bf16 v[74:77], v[184:187], v[232:235], v[74:77]
	v_mfma_f32_16x16x32_bf16 v[70:73], v[188:191], v[228:231], v[70:73]
	v_mfma_f32_16x16x32_bf16 v[70:73], v[192:195], v[232:235], v[70:73]
	v_mfma_f32_16x16x32_bf16 v[66:69], v[196:199], v[228:231], v[66:69]
	v_mfma_f32_16x16x32_bf16 v[66:69], v[200:203], v[232:235], v[66:69]
	s_setprio 0
	s_barrier
	s_add_i32 s88, s70, s27
	s_add_u32 s98, s74, 0x80
	s_addc_u32 s99, s75, 0
	s_mov_b32 m0, s88
	ds_read_b128 v[204:207], v169 offset:16384
	ds_read_b128 v[208:211], v169 offset:17408
	ds_read_b128 v[212:215], v169 offset:18432
	ds_read_b128 v[216:219], v169 offset:19456
	ds_read_b128 v[220:223], v169 offset:20480
	ds_read_b128 v[224:227], v169 offset:21504
	ds_read_b128 v[228:231], v169 offset:22528
	ds_read_b128 v[232:235], v169 offset:23552
	global_load_lds_dwordx4 v132, s[74:75]
	s_add_i32 m0, s88, 0x2000
	s_add_u32 s88, s74, 0x100000
	s_addc_u32 s89, s75, 0
	s_add_i32 s90, s71, s27
	global_load_lds_dwordx4 v136, s[74:75]
	s_mov_b32 m0, s90
	global_load_lds_dwordx4 v132, s[88:89]
	s_add_i32 m0, s90, 0x2000
	s_nop 0
	global_load_lds_dwordx4 v136, s[88:89]
	s_add_u32 s100, s76, 0x80
	s_addc_u32 s101, s77, 0
	s_mov_b32 m0, s59
	s_nop 0
	global_load_lds_dwordx4 v130, s[76:77]
	s_mov_b32 m0, s62
	s_nop 0
	global_load_lds_dwordx4 v134, s[76:77]
	s_waitcnt vmcnt(8)
	s_waitcnt lgkmcnt(0)
	s_barrier
	s_setprio 1
	v_mfma_f32_16x16x32_bf16 v[62:65], v[150:153], v[204:207], v[62:65]
	v_mfma_f32_16x16x32_bf16 v[62:65], v[172:175], v[208:211], v[62:65]
	v_mfma_f32_16x16x32_bf16 v[58:61], v[176:179], v[204:207], v[58:61]
	v_mfma_f32_16x16x32_bf16 v[58:61], v[184:187], v[208:211], v[58:61]
	v_mfma_f32_16x16x32_bf16 v[54:57], v[188:191], v[204:207], v[54:57]
	v_mfma_f32_16x16x32_bf16 v[54:57], v[192:195], v[208:211], v[54:57]
	v_mfma_f32_16x16x32_bf16 v[46:49], v[196:199], v[204:207], v[46:49]
	v_mfma_f32_16x16x32_bf16 v[46:49], v[200:203], v[208:211], v[46:49]
	v_mfma_f32_16x16x32_bf16 v[50:53], v[150:153], v[212:215], v[50:53]
	v_mfma_f32_16x16x32_bf16 v[50:53], v[172:175], v[216:219], v[50:53]
	v_mfma_f32_16x16x32_bf16 v[42:45], v[176:179], v[212:215], v[42:45]
	v_mfma_f32_16x16x32_bf16 v[42:45], v[184:187], v[216:219], v[42:45]
	v_mfma_f32_16x16x32_bf16 v[38:41], v[188:191], v[212:215], v[38:41]
	v_mfma_f32_16x16x32_bf16 v[38:41], v[192:195], v[216:219], v[38:41]
	v_mfma_f32_16x16x32_bf16 v[30:33], v[196:199], v[212:215], v[30:33]
	v_mfma_f32_16x16x32_bf16 v[30:33], v[200:203], v[216:219], v[30:33]
	v_mfma_f32_16x16x32_bf16 v[34:37], v[150:153], v[220:223], v[34:37]
	v_mfma_f32_16x16x32_bf16 v[34:37], v[172:175], v[224:227], v[34:37]
	v_mfma_f32_16x16x32_bf16 v[26:29], v[176:179], v[220:223], v[26:29]
	v_mfma_f32_16x16x32_bf16 v[26:29], v[184:187], v[224:227], v[26:29]
	v_mfma_f32_16x16x32_bf16 v[22:25], v[188:191], v[220:223], v[22:25]
	v_mfma_f32_16x16x32_bf16 v[22:25], v[192:195], v[224:227], v[22:25]
	v_mfma_f32_16x16x32_bf16 v[14:17], v[196:199], v[220:223], v[14:17]
	v_mfma_f32_16x16x32_bf16 v[14:17], v[200:203], v[224:227], v[14:17]
	v_mfma_f32_16x16x32_bf16 v[18:21], v[150:153], v[228:231], v[18:21]
	v_mfma_f32_16x16x32_bf16 v[18:21], v[172:175], v[232:235], v[18:21]
	v_mfma_f32_16x16x32_bf16 v[10:13], v[176:179], v[228:231], v[10:13]
	v_mfma_f32_16x16x32_bf16 v[10:13], v[184:187], v[232:235], v[10:13]
	v_mfma_f32_16x16x32_bf16 v[6:9], v[188:191], v[228:231], v[6:9]
	v_mfma_f32_16x16x32_bf16 v[6:9], v[192:195], v[232:235], v[6:9]
	v_mfma_f32_16x16x32_bf16 v[2:5], v[196:199], v[228:231], v[2:5]
	v_mfma_f32_16x16x32_bf16 v[2:5], v[200:203], v[232:235], v[2:5]
	s_setprio 0
	s_barrier
	s_add_i32 s88, 0, 0x18000
	v_add_u32_e32 v140, s88, v163
	s_add_i32 s89, 0, 0x1c000
	ds_read_b128 v[150:153], v140
	ds_read_b128 v[172:175], v140 offset:1024
	ds_read_b128 v[176:179], v140 offset:2048
	ds_read_b128 v[184:187], v140 offset:3072
	v_add_u32_e32 v140, s89, v163
	ds_read_b128 v[188:191], v140
	ds_read_b128 v[192:195], v140 offset:1024
	ds_read_b128 v[196:199], v140 offset:2048
	ds_read_b128 v[200:203], v140 offset:3072
	s_add_u32 s76, s76, 0x100000
	s_addc_u32 s77, s77, 0
	s_mov_b32 m0, s63
	ds_read_b128 v[204:207], v169 offset:32768
	ds_read_b128 v[208:211], v169 offset:33792
	ds_read_b128 v[212:215], v169 offset:34816
	ds_read_b128 v[216:219], v169 offset:35840
	ds_read_b128 v[220:223], v169 offset:36864
	ds_read_b128 v[224:227], v169 offset:37888
	ds_read_b128 v[228:231], v169 offset:38912
	ds_read_b128 v[232:235], v169 offset:39936
	global_load_lds_dwordx4 v130, s[76:77]
	s_mov_b32 m0, s65
	s_nop 0
	global_load_lds_dwordx4 v134, s[76:77]
	s_waitcnt vmcnt(8)
	s_waitcnt lgkmcnt(0)
	s_barrier
	s_setprio 1
	v_mfma_f32_16x16x32_bf16 v[126:129], v[150:153], v[204:207], v[126:129]
	v_mfma_f32_16x16x32_bf16 v[126:129], v[172:175], v[208:211], v[126:129]
	v_mfma_f32_16x16x32_bf16 v[122:125], v[176:179], v[204:207], v[122:125]
	v_mfma_f32_16x16x32_bf16 v[122:125], v[184:187], v[208:211], v[122:125]
	v_mfma_f32_16x16x32_bf16 v[118:121], v[188:191], v[204:207], v[118:121]
	v_mfma_f32_16x16x32_bf16 v[118:121], v[192:195], v[208:211], v[118:121]
	v_mfma_f32_16x16x32_bf16 v[114:117], v[196:199], v[204:207], v[114:117]
	v_mfma_f32_16x16x32_bf16 v[114:117], v[200:203], v[208:211], v[114:117]
	v_mfma_f32_16x16x32_bf16 v[110:113], v[150:153], v[212:215], v[110:113]
	v_mfma_f32_16x16x32_bf16 v[110:113], v[172:175], v[216:219], v[110:113]
	v_mfma_f32_16x16x32_bf16 v[106:109], v[176:179], v[212:215], v[106:109]
	v_mfma_f32_16x16x32_bf16 v[106:109], v[184:187], v[216:219], v[106:109]
	v_mfma_f32_16x16x32_bf16 v[102:105], v[188:191], v[212:215], v[102:105]
	v_mfma_f32_16x16x32_bf16 v[102:105], v[192:195], v[216:219], v[102:105]
	v_mfma_f32_16x16x32_bf16 v[98:101], v[196:199], v[212:215], v[98:101]
	v_mfma_f32_16x16x32_bf16 v[98:101], v[200:203], v[216:219], v[98:101]
	v_mfma_f32_16x16x32_bf16 v[94:97], v[150:153], v[220:223], v[94:97]
	v_mfma_f32_16x16x32_bf16 v[94:97], v[172:175], v[224:227], v[94:97]
	v_mfma_f32_16x16x32_bf16 v[90:93], v[176:179], v[220:223], v[90:93]
	v_mfma_f32_16x16x32_bf16 v[90:93], v[184:187], v[224:227], v[90:93]
	v_mfma_f32_16x16x32_bf16 v[86:89], v[188:191], v[220:223], v[86:89]
	v_mfma_f32_16x16x32_bf16 v[86:89], v[192:195], v[224:227], v[86:89]
	v_mfma_f32_16x16x32_bf16 v[82:85], v[196:199], v[220:223], v[82:85]
	v_mfma_f32_16x16x32_bf16 v[82:85], v[200:203], v[224:227], v[82:85]
	v_mfma_f32_16x16x32_bf16 v[78:81], v[150:153], v[228:231], v[78:81]
	v_mfma_f32_16x16x32_bf16 v[78:81], v[172:175], v[232:235], v[78:81]
	v_mfma_f32_16x16x32_bf16 v[74:77], v[176:179], v[228:231], v[74:77]
	v_mfma_f32_16x16x32_bf16 v[74:77], v[184:187], v[232:235], v[74:77]
	v_mfma_f32_16x16x32_bf16 v[70:73], v[188:191], v[228:231], v[70:73]
	v_mfma_f32_16x16x32_bf16 v[70:73], v[192:195], v[232:235], v[70:73]
	v_mfma_f32_16x16x32_bf16 v[66:69], v[196:199], v[228:231], v[66:69]
	v_mfma_f32_16x16x32_bf16 v[66:69], v[200:203], v[232:235], v[66:69]
	s_setprio 0
	s_barrier
	s_add_i32 s76, s88, s27
	s_mov_b32 m0, s76
	ds_read_b128 v[204:207], v169 offset:49152
	ds_read_b128 v[208:211], v169 offset:50176
	ds_read_b128 v[212:215], v169 offset:51200
	ds_read_b128 v[216:219], v169 offset:52224
	ds_read_b128 v[220:223], v169 offset:53248
	ds_read_b128 v[224:227], v169 offset:54272
	ds_read_b128 v[228:231], v169 offset:55296
	ds_read_b128 v[232:235], v169 offset:56320
	global_load_lds_dwordx4 v132, s[98:99]
	s_add_i32 m0, s76, 0x2000
	s_add_u32 s74, s74, 0x100080
	s_addc_u32 s75, s75, 0
	s_add_i32 s76, s89, s27
	global_load_lds_dwordx4 v136, s[98:99]
	s_mov_b32 m0, s76
	s_nop 0
	global_load_lds_dwordx4 v132, s[74:75]
	s_add_i32 m0, s76, 0x2000
	s_nop 0
	global_load_lds_dwordx4 v136, s[74:75]
	s_mov_b32 m0, s67
	s_nop 0
	global_load_lds_dwordx4 v130, s[100:101]
	s_mov_b32 m0, s68
	s_nop 0
	global_load_lds_dwordx4 v134, s[100:101]
	s_waitcnt vmcnt(8)
	s_waitcnt lgkmcnt(0)
	s_barrier
	s_setprio 1
	v_mfma_f32_16x16x32_bf16 v[62:65], v[150:153], v[204:207], v[62:65]
	v_mfma_f32_16x16x32_bf16 v[62:65], v[172:175], v[208:211], v[62:65]
	v_mfma_f32_16x16x32_bf16 v[58:61], v[176:179], v[204:207], v[58:61]
	v_mfma_f32_16x16x32_bf16 v[58:61], v[184:187], v[208:211], v[58:61]
	v_mfma_f32_16x16x32_bf16 v[54:57], v[188:191], v[204:207], v[54:57]
	v_mfma_f32_16x16x32_bf16 v[54:57], v[192:195], v[208:211], v[54:57]
	v_mfma_f32_16x16x32_bf16 v[46:49], v[196:199], v[204:207], v[46:49]
	v_mfma_f32_16x16x32_bf16 v[46:49], v[200:203], v[208:211], v[46:49]
	v_mfma_f32_16x16x32_bf16 v[50:53], v[150:153], v[212:215], v[50:53]
	v_mfma_f32_16x16x32_bf16 v[50:53], v[172:175], v[216:219], v[50:53]
	v_mfma_f32_16x16x32_bf16 v[42:45], v[176:179], v[212:215], v[42:45]
	v_mfma_f32_16x16x32_bf16 v[42:45], v[184:187], v[216:219], v[42:45]
	v_mfma_f32_16x16x32_bf16 v[38:41], v[188:191], v[212:215], v[38:41]
	v_mfma_f32_16x16x32_bf16 v[38:41], v[192:195], v[216:219], v[38:41]
	v_mfma_f32_16x16x32_bf16 v[30:33], v[196:199], v[212:215], v[30:33]
	v_mfma_f32_16x16x32_bf16 v[30:33], v[200:203], v[216:219], v[30:33]
	v_mfma_f32_16x16x32_bf16 v[34:37], v[150:153], v[220:223], v[34:37]
	v_mfma_f32_16x16x32_bf16 v[34:37], v[172:175], v[224:227], v[34:37]
	v_mfma_f32_16x16x32_bf16 v[26:29], v[176:179], v[220:223], v[26:29]
	v_mfma_f32_16x16x32_bf16 v[26:29], v[184:187], v[224:227], v[26:29]
	v_mfma_f32_16x16x32_bf16 v[22:25], v[188:191], v[220:223], v[22:25]
	v_mfma_f32_16x16x32_bf16 v[22:25], v[192:195], v[224:227], v[22:25]
	v_mfma_f32_16x16x32_bf16 v[14:17], v[196:199], v[220:223], v[14:17]
	v_mfma_f32_16x16x32_bf16 v[14:17], v[200:203], v[224:227], v[14:17]
	v_mfma_f32_16x16x32_bf16 v[18:21], v[150:153], v[228:231], v[18:21]
	v_mfma_f32_16x16x32_bf16 v[18:21], v[172:175], v[232:235], v[18:21]
	v_mfma_f32_16x16x32_bf16 v[10:13], v[176:179], v[228:231], v[10:13]
	v_mfma_f32_16x16x32_bf16 v[10:13], v[184:187], v[232:235], v[10:13]
	v_mfma_f32_16x16x32_bf16 v[6:9], v[188:191], v[228:231], v[6:9]
	v_mfma_f32_16x16x32_bf16 v[6:9], v[192:195], v[232:235], v[6:9]
	v_mfma_f32_16x16x32_bf16 v[2:5], v[196:199], v[228:231], v[2:5]
	v_mfma_f32_16x16x32_bf16 v[2:5], v[200:203], v[232:235], v[2:5]
	s_setprio 0
	s_barrier
	s_add_i32 s87, s87, 2
	s_add_u32 s6, s6, 0x100
	s_addc_u32 s7, s7, 0
	s_add_u32 s85, s85, 0x100
	s_addc_u32 s86, s86, 0
	s_cmp_gt_u32 s87, 61
	s_cbranch_scc0 .LBB0_2464
	s_and_b64 vcc, exec, s[38:39]
	s_cbranch_vccz .LBB0_2467
	s_barrier

.LBB0_2494:
	ds_read_b128 v[160:163], v155
	ds_read_b128 v[164:167], v155 offset:1024
	ds_read_b128 v[168:171], v155 offset:2048
	ds_read_b128 v[172:175], v155 offset:3072
	ds_read_b128 v[176:179], v156
	ds_read_b128 v[184:187], v156 offset:1024
	ds_read_b128 v[188:191], v156 offset:2048
	ds_read_b128 v[192:195], v156 offset:3072
	s_add_u32 s48, s6, 0xfff00080
	s_addc_u32 s49, s7, -1
	s_cmp_eq_u32 s89, 60
	s_cselect_b32 s51, s43, s49
	s_cselect_b32 s50, s85, s48
	s_cselect_b32 s49, s41, s88
	s_cselect_b32 s48, s86, s87
	s_add_i32 m0, s63, 0xc000
	ds_read_b128 v[196:199], v157
	ds_read_b128 v[200:203], v157 offset:1024
	ds_read_b128 v[204:207], v157 offset:2048
	ds_read_b128 v[208:211], v157 offset:3072
	ds_read_b128 v[212:215], v157 offset:4096
	ds_read_b128 v[216:219], v157 offset:5120
	ds_read_b128 v[220:223], v157 offset:6144
	ds_read_b128 v[224:227], v157 offset:7168
	global_load_lds_dwordx4 v140, s[6:7]
	s_add_i32 m0, s63, 0xe000
	s_nop 0
	global_load_lds_dwordx4 v142, s[6:7]
	s_waitcnt vmcnt(8)
	s_waitcnt lgkmcnt(0)
	s_barrier
	s_setprio 1
	v_mfma_f32_16x16x32_bf16 v[126:129], v[160:163], v[196:199], v[126:129]
	v_mfma_f32_16x16x32_bf16 v[126:129], v[164:167], v[200:203], v[126:129]
	v_mfma_f32_16x16x32_bf16 v[122:125], v[168:171], v[196:199], v[122:125]
	v_mfma_f32_16x16x32_bf16 v[122:125], v[172:175], v[200:203], v[122:125]
	v_mfma_f32_16x16x32_bf16 v[118:121], v[176:179], v[196:199], v[118:121]
	v_mfma_f32_16x16x32_bf16 v[118:121], v[184:187], v[200:203], v[118:121]
	v_mfma_f32_16x16x32_bf16 v[114:117], v[188:191], v[196:199], v[114:117]
	v_mfma_f32_16x16x32_bf16 v[114:117], v[192:195], v[200:203], v[114:117]
	v_mfma_f32_16x16x32_bf16 v[110:113], v[160:163], v[204:207], v[110:113]
	v_mfma_f32_16x16x32_bf16 v[110:113], v[164:167], v[208:211], v[110:113]
	v_mfma_f32_16x16x32_bf16 v[106:109], v[168:171], v[204:207], v[106:109]
	v_mfma_f32_16x16x32_bf16 v[106:109], v[172:175], v[208:211], v[106:109]
	v_mfma_f32_16x16x32_bf16 v[102:105], v[176:179], v[204:207], v[102:105]
	v_mfma_f32_16x16x32_bf16 v[102:105], v[184:187], v[208:211], v[102:105]
	v_mfma_f32_16x16x32_bf16 v[98:101], v[188:191], v[204:207], v[98:101]
	v_mfma_f32_16x16x32_bf16 v[98:101], v[192:195], v[208:211], v[98:101]
	v_mfma_f32_16x16x32_bf16 v[94:97], v[160:163], v[212:215], v[94:97]
	v_mfma_f32_16x16x32_bf16 v[94:97], v[164:167], v[216:219], v[94:97]
	v_mfma_f32_16x16x32_bf16 v[90:93], v[168:171], v[212:215], v[90:93]
	v_mfma_f32_16x16x32_bf16 v[90:93], v[172:175], v[216:219], v[90:93]
	v_mfma_f32_16x16x32_bf16 v[86:89], v[176:179], v[212:215], v[86:89]
	v_mfma_f32_16x16x32_bf16 v[86:89], v[184:187], v[216:219], v[86:89]
	v_mfma_f32_16x16x32_bf16 v[82:85], v[188:191], v[212:215], v[82:85]
	v_mfma_f32_16x16x32_bf16 v[82:85], v[192:195], v[216:219], v[82:85]
	v_mfma_f32_16x16x32_bf16 v[78:81], v[160:163], v[220:223], v[78:81]
	v_mfma_f32_16x16x32_bf16 v[78:81], v[164:167], v[224:227], v[78:81]
	v_mfma_f32_16x16x32_bf16 v[74:77], v[168:171], v[220:223], v[74:77]
	v_mfma_f32_16x16x32_bf16 v[74:77], v[172:175], v[224:227], v[74:77]
	v_mfma_f32_16x16x32_bf16 v[70:73], v[176:179], v[220:223], v[70:73]
	v_mfma_f32_16x16x32_bf16 v[70:73], v[184:187], v[224:227], v[70:73]
	v_mfma_f32_16x16x32_bf16 v[66:69], v[188:191], v[220:223], v[66:69]
	v_mfma_f32_16x16x32_bf16 v[66:69], v[192:195], v[224:227], v[66:69]
	s_setprio 0
	s_barrier
	s_add_i32 s90, s73, s27
	s_add_u32 s98, s48, 0x80
	s_addc_u32 s99, s49, 0
	s_mov_b32 m0, s90
	ds_read_b128 v[196:199], v157 offset:16384
	ds_read_b128 v[200:203], v157 offset:17408
	ds_read_b128 v[204:207], v157 offset:18432
	ds_read_b128 v[208:211], v157 offset:19456
	ds_read_b128 v[212:215], v157 offset:20480
	ds_read_b128 v[216:219], v157 offset:21504
	ds_read_b128 v[220:223], v157 offset:22528
	ds_read_b128 v[224:227], v157 offset:23552
	global_load_lds_dwordx4 v132, s[48:49]
	s_add_i32 m0, s90, 0x2000
	s_add_u32 s90, s48, 0x100000
	s_addc_u32 s91, s49, 0
	s_add_i32 s92, s74, s27
	global_load_lds_dwordx4 v136, s[48:49]
	s_mov_b32 m0, s92
	global_load_lds_dwordx4 v132, s[90:91]
	s_add_i32 m0, s92, 0x2000
	s_nop 0
	global_load_lds_dwordx4 v136, s[90:91]
	s_add_u32 s100, s50, 0x80
	s_addc_u32 s101, s51, 0
	s_mov_b32 m0, s63
	s_nop 0
	global_load_lds_dwordx4 v130, s[50:51]
	s_mov_b32 m0, s65
	s_nop 0
	global_load_lds_dwordx4 v134, s[50:51]
	s_waitcnt vmcnt(8)
	s_waitcnt lgkmcnt(0)
	s_barrier
	s_setprio 1
	v_mfma_f32_16x16x32_bf16 v[62:65], v[160:163], v[196:199], v[62:65]
	v_mfma_f32_16x16x32_bf16 v[62:65], v[164:167], v[200:203], v[62:65]
	v_mfma_f32_16x16x32_bf16 v[58:61], v[168:171], v[196:199], v[58:61]
	v_mfma_f32_16x16x32_bf16 v[58:61], v[172:175], v[200:203], v[58:61]
	v_mfma_f32_16x16x32_bf16 v[54:57], v[176:179], v[196:199], v[54:57]
	v_mfma_f32_16x16x32_bf16 v[54:57], v[184:187], v[200:203], v[54:57]
	v_mfma_f32_16x16x32_bf16 v[46:49], v[188:191], v[196:199], v[46:49]
	v_mfma_f32_16x16x32_bf16 v[46:49], v[192:195], v[200:203], v[46:49]
	v_mfma_f32_16x16x32_bf16 v[50:53], v[160:163], v[204:207], v[50:53]
	v_mfma_f32_16x16x32_bf16 v[50:53], v[164:167], v[208:211], v[50:53]
	v_mfma_f32_16x16x32_bf16 v[42:45], v[168:171], v[204:207], v[42:45]
	v_mfma_f32_16x16x32_bf16 v[42:45], v[172:175], v[208:211], v[42:45]
	v_mfma_f32_16x16x32_bf16 v[38:41], v[176:179], v[204:207], v[38:41]
	v_mfma_f32_16x16x32_bf16 v[38:41], v[184:187], v[208:211], v[38:41]
	v_mfma_f32_16x16x32_bf16 v[30:33], v[188:191], v[204:207], v[30:33]
	v_mfma_f32_16x16x32_bf16 v[30:33], v[192:195], v[208:211], v[30:33]
	v_mfma_f32_16x16x32_bf16 v[34:37], v[160:163], v[212:215], v[34:37]
	v_mfma_f32_16x16x32_bf16 v[34:37], v[164:167], v[216:219], v[34:37]
	v_mfma_f32_16x16x32_bf16 v[26:29], v[168:171], v[212:215], v[26:29]
	v_mfma_f32_16x16x32_bf16 v[26:29], v[172:175], v[216:219], v[26:29]
	v_mfma_f32_16x16x32_bf16 v[22:25], v[176:179], v[212:215], v[22:25]
	v_mfma_f32_16x16x32_bf16 v[22:25], v[184:187], v[216:219], v[22:25]
	v_mfma_f32_16x16x32_bf16 v[14:17], v[188:191], v[212:215], v[14:17]
	v_mfma_f32_16x16x32_bf16 v[14:17], v[192:195], v[216:219], v[14:17]
	v_mfma_f32_16x16x32_bf16 v[18:21], v[160:163], v[220:223], v[18:21]
	v_mfma_f32_16x16x32_bf16 v[18:21], v[164:167], v[224:227], v[18:21]
	v_mfma_f32_16x16x32_bf16 v[10:13], v[168:171], v[220:223], v[10:13]
	v_mfma_f32_16x16x32_bf16 v[10:13], v[172:175], v[224:227], v[10:13]
	v_mfma_f32_16x16x32_bf16 v[6:9], v[176:179], v[220:223], v[6:9]
	v_mfma_f32_16x16x32_bf16 v[6:9], v[184:187], v[224:227], v[6:9]
	v_mfma_f32_16x16x32_bf16 v[2:5], v[188:191], v[220:223], v[2:5]
	v_mfma_f32_16x16x32_bf16 v[2:5], v[192:195], v[224:227], v[2:5]
	s_setprio 0
	s_barrier
	s_add_i32 s90, 0, 0x18000
	v_add_u32_e32 v138, s90, v151
	s_add_i32 s91, 0, 0x1c000
	ds_read_b128 v[160:163], v138
	ds_read_b128 v[164:167], v138 offset:1024
	ds_read_b128 v[168:171], v138 offset:2048
	ds_read_b128 v[172:175], v138 offset:3072
	v_add_u32_e32 v138, s91, v151
	ds_read_b128 v[176:179], v138
	ds_read_b128 v[184:187], v138 offset:1024
	ds_read_b128 v[188:191], v138 offset:2048
	ds_read_b128 v[192:195], v138 offset:3072
	s_add_u32 s50, s50, 0x100000
	s_addc_u32 s51, s51, 0
	s_mov_b32 m0, s66
	ds_read_b128 v[196:199], v157 offset:32768
	ds_read_b128 v[200:203], v157 offset:33792
	ds_read_b128 v[204:207], v157 offset:34816
	ds_read_b128 v[208:211], v157 offset:35840
	ds_read_b128 v[212:215], v157 offset:36864
	ds_read_b128 v[216:219], v157 offset:37888
	ds_read_b128 v[220:223], v157 offset:38912
	ds_read_b128 v[224:227], v157 offset:39936
	global_load_lds_dwordx4 v130, s[50:51]
	s_mov_b32 m0, s67
	s_nop 0
	global_load_lds_dwordx4 v134, s[50:51]
	s_waitcnt vmcnt(8)
	s_waitcnt lgkmcnt(0)
	s_barrier
	s_setprio 1
	v_mfma_f32_16x16x32_bf16 v[126:129], v[160:163], v[196:199], v[126:129]
	v_mfma_f32_16x16x32_bf16 v[126:129], v[164:167], v[200:203], v[126:129]
	v_mfma_f32_16x16x32_bf16 v[122:125], v[168:171], v[196:199], v[122:125]
	v_mfma_f32_16x16x32_bf16 v[122:125], v[172:175], v[200:203], v[122:125]
	v_mfma_f32_16x16x32_bf16 v[118:121], v[176:179], v[196:199], v[118:121]
	v_mfma_f32_16x16x32_bf16 v[118:121], v[184:187], v[200:203], v[118:121]
	v_mfma_f32_16x16x32_bf16 v[114:117], v[188:191], v[196:199], v[114:117]
	v_mfma_f32_16x16x32_bf16 v[114:117], v[192:195], v[200:203], v[114:117]
	v_mfma_f32_16x16x32_bf16 v[110:113], v[160:163], v[204:207], v[110:113]
	v_mfma_f32_16x16x32_bf16 v[110:113], v[164:167], v[208:211], v[110:113]
	v_mfma_f32_16x16x32_bf16 v[106:109], v[168:171], v[204:207], v[106:109]
	v_mfma_f32_16x16x32_bf16 v[106:109], v[172:175], v[208:211], v[106:109]
	v_mfma_f32_16x16x32_bf16 v[102:105], v[176:179], v[204:207], v[102:105]
	v_mfma_f32_16x16x32_bf16 v[102:105], v[184:187], v[208:211], v[102:105]
	v_mfma_f32_16x16x32_bf16 v[98:101], v[188:191], v[204:207], v[98:101]
	v_mfma_f32_16x16x32_bf16 v[98:101], v[192:195], v[208:211], v[98:101]
	v_mfma_f32_16x16x32_bf16 v[94:97], v[160:163], v[212:215], v[94:97]
	v_mfma_f32_16x16x32_bf16 v[94:97], v[164:167], v[216:219], v[94:97]
	v_mfma_f32_16x16x32_bf16 v[90:93], v[168:171], v[212:215], v[90:93]
	v_mfma_f32_16x16x32_bf16 v[90:93], v[172:175], v[216:219], v[90:93]
	v_mfma_f32_16x16x32_bf16 v[86:89], v[176:179], v[212:215], v[86:89]
	v_mfma_f32_16x16x32_bf16 v[86:89], v[184:187], v[216:219], v[86:89]
	v_mfma_f32_16x16x32_bf16 v[82:85], v[188:191], v[212:215], v[82:85]
	v_mfma_f32_16x16x32_bf16 v[82:85], v[192:195], v[216:219], v[82:85]
	v_mfma_f32_16x16x32_bf16 v[78:81], v[160:163], v[220:223], v[78:81]
	v_mfma_f32_16x16x32_bf16 v[78:81], v[164:167], v[224:227], v[78:81]
	v_mfma_f32_16x16x32_bf16 v[74:77], v[168:171], v[220:223], v[74:77]
	v_mfma_f32_16x16x32_bf16 v[74:77], v[172:175], v[224:227], v[74:77]
	v_mfma_f32_16x16x32_bf16 v[70:73], v[176:179], v[220:223], v[70:73]
	v_mfma_f32_16x16x32_bf16 v[70:73], v[184:187], v[224:227], v[70:73]
	v_mfma_f32_16x16x32_bf16 v[66:69], v[188:191], v[220:223], v[66:69]
	v_mfma_f32_16x16x32_bf16 v[66:69], v[192:195], v[224:227], v[66:69]
	s_setprio 0
	s_barrier
	s_add_i32 s50, s90, s27
	s_mov_b32 m0, s50
	ds_read_b128 v[196:199], v157 offset:49152
	ds_read_b128 v[200:203], v157 offset:50176
	ds_read_b128 v[204:207], v157 offset:51200
	ds_read_b128 v[208:211], v157 offset:52224
	ds_read_b128 v[212:215], v157 offset:53248
	ds_read_b128 v[216:219], v157 offset:54272
	ds_read_b128 v[220:223], v157 offset:55296
	ds_read_b128 v[224:227], v157 offset:56320
	global_load_lds_dwordx4 v132, s[98:99]
	s_add_i32 m0, s50, 0x2000
	s_add_u32 s48, s48, 0x100080
	s_addc_u32 s49, s49, 0
	s_add_i32 s50, s91, s27
	global_load_lds_dwordx4 v136, s[98:99]
	s_mov_b32 m0, s50
	s_nop 0
	global_load_lds_dwordx4 v132, s[48:49]
	s_add_i32 m0, s50, 0x2000
	s_nop 0
	global_load_lds_dwordx4 v136, s[48:49]
	s_mov_b32 m0, s69
	s_nop 0
	global_load_lds_dwordx4 v130, s[100:101]
	s_mov_b32 m0, s70
	s_nop 0
	global_load_lds_dwordx4 v134, s[100:101]
	s_waitcnt vmcnt(8)
	s_waitcnt lgkmcnt(0)
	s_barrier
	s_setprio 1
	v_mfma_f32_16x16x32_bf16 v[62:65], v[160:163], v[196:199], v[62:65]
	v_mfma_f32_16x16x32_bf16 v[62:65], v[164:167], v[200:203], v[62:65]
	v_mfma_f32_16x16x32_bf16 v[58:61], v[168:171], v[196:199], v[58:61]
	v_mfma_f32_16x16x32_bf16 v[58:61], v[172:175], v[200:203], v[58:61]
	v_mfma_f32_16x16x32_bf16 v[54:57], v[176:179], v[196:199], v[54:57]
	v_mfma_f32_16x16x32_bf16 v[54:57], v[184:187], v[200:203], v[54:57]
	v_mfma_f32_16x16x32_bf16 v[46:49], v[188:191], v[196:199], v[46:49]
	v_mfma_f32_16x16x32_bf16 v[46:49], v[192:195], v[200:203], v[46:49]
	v_mfma_f32_16x16x32_bf16 v[50:53], v[160:163], v[204:207], v[50:53]
	v_mfma_f32_16x16x32_bf16 v[50:53], v[164:167], v[208:211], v[50:53]
	v_mfma_f32_16x16x32_bf16 v[42:45], v[168:171], v[204:207], v[42:45]
	v_mfma_f32_16x16x32_bf16 v[42:45], v[172:175], v[208:211], v[42:45]
	v_mfma_f32_16x16x32_bf16 v[38:41], v[176:179], v[204:207], v[38:41]
	v_mfma_f32_16x16x32_bf16 v[38:41], v[184:187], v[208:211], v[38:41]
	v_mfma_f32_16x16x32_bf16 v[30:33], v[188:191], v[204:207], v[30:33]
	v_mfma_f32_16x16x32_bf16 v[30:33], v[192:195], v[208:211], v[30:33]
	v_mfma_f32_16x16x32_bf16 v[34:37], v[160:163], v[212:215], v[34:37]
	v_mfma_f32_16x16x32_bf16 v[34:37], v[164:167], v[216:219], v[34:37]
	v_mfma_f32_16x16x32_bf16 v[26:29], v[168:171], v[212:215], v[26:29]
	v_mfma_f32_16x16x32_bf16 v[26:29], v[172:175], v[216:219], v[26:29]
	v_mfma_f32_16x16x32_bf16 v[22:25], v[176:179], v[212:215], v[22:25]
	v_mfma_f32_16x16x32_bf16 v[22:25], v[184:187], v[216:219], v[22:25]
	v_mfma_f32_16x16x32_bf16 v[14:17], v[188:191], v[212:215], v[14:17]
	v_mfma_f32_16x16x32_bf16 v[14:17], v[192:195], v[216:219], v[14:17]
	v_mfma_f32_16x16x32_bf16 v[18:21], v[160:163], v[220:223], v[18:21]
	v_mfma_f32_16x16x32_bf16 v[18:21], v[164:167], v[224:227], v[18:21]
	v_mfma_f32_16x16x32_bf16 v[10:13], v[168:171], v[220:223], v[10:13]
	v_mfma_f32_16x16x32_bf16 v[10:13], v[172:175], v[224:227], v[10:13]
	v_mfma_f32_16x16x32_bf16 v[6:9], v[176:179], v[220:223], v[6:9]
	v_mfma_f32_16x16x32_bf16 v[6:9], v[184:187], v[224:227], v[6:9]
	v_mfma_f32_16x16x32_bf16 v[2:5], v[188:191], v[220:223], v[2:5]
	v_mfma_f32_16x16x32_bf16 v[2:5], v[192:195], v[224:227], v[2:5]
	s_setprio 0
	s_barrier
	s_add_i32 s89, s89, 2
	s_add_u32 s6, s6, 0x100
	s_addc_u32 s7, s7, 0
	s_add_u32 s87, s87, 0x100
	s_addc_u32 s88, s88, 0
	s_cmp_gt_u32 s89, 61
	s_cbranch_scc0 .LBB0_2494
	s_and_b64 vcc, exec, s[38:39]
	s_cbranch_vccz .LBB0_2497
	s_barrier

.LBB0_2635:
	ds_read_b128 v[130:133], v163
	ds_read_b128 v[134:137], v163 offset:1024
	ds_read_b128 v[138:141], v163 offset:2048
	ds_read_b128 v[142:145], v163 offset:3072
	ds_read_b128 v[146:149], v188
	ds_read_b128 v[150:153], v188 offset:1024
	ds_read_b128 v[174:177], v188 offset:2048
	ds_read_b128 v[178:181], v188 offset:3072
	s_add_u32 s48, s46, 0xfff00080
	s_addc_u32 s49, s47, -1
	s_cmp_eq_u32 s73, 60
	s_cselect_b32 s51, s22, s49
	s_cselect_b32 s50, s41, s48
	s_cselect_b32 s49, s39, s72
	s_cselect_b32 s48, s70, s71
	s_add_i32 m0, s13, 0xc000
	ds_read_b128 v[184:187], v189
	ds_read_b128 v[192:195], v189 offset:1024
	ds_read_b128 v[196:199], v189 offset:2048
	ds_read_b128 v[200:203], v189 offset:3072
	ds_read_b128 v[204:207], v189 offset:4096
	ds_read_b128 v[208:211], v189 offset:5120
	ds_read_b128 v[212:215], v189 offset:6144
	ds_read_b128 v[216:219], v189 offset:7168
	global_load_lds_dwordx4 v166, s[46:47]
	s_add_i32 m0, s13, 0xe000
	s_nop 0
	global_load_lds_dwordx4 v168, s[46:47]
	s_waitcnt vmcnt(8)
	s_waitcnt lgkmcnt(0)
	s_barrier
	s_setprio 1
	v_mfma_f32_16x16x32_bf16 v[126:129], v[130:133], v[184:187], v[126:129]
	v_mfma_f32_16x16x32_bf16 v[126:129], v[134:137], v[192:195], v[126:129]
	v_mfma_f32_16x16x32_bf16 v[122:125], v[138:141], v[184:187], v[122:125]
	v_mfma_f32_16x16x32_bf16 v[122:125], v[142:145], v[192:195], v[122:125]
	v_mfma_f32_16x16x32_bf16 v[118:121], v[146:149], v[184:187], v[118:121]
	v_mfma_f32_16x16x32_bf16 v[118:121], v[150:153], v[192:195], v[118:121]
	v_mfma_f32_16x16x32_bf16 v[114:117], v[174:177], v[184:187], v[114:117]
	v_mfma_f32_16x16x32_bf16 v[114:117], v[178:181], v[192:195], v[114:117]
	v_mfma_f32_16x16x32_bf16 v[110:113], v[130:133], v[196:199], v[110:113]
	v_mfma_f32_16x16x32_bf16 v[110:113], v[134:137], v[200:203], v[110:113]
	v_mfma_f32_16x16x32_bf16 v[106:109], v[138:141], v[196:199], v[106:109]
	v_mfma_f32_16x16x32_bf16 v[106:109], v[142:145], v[200:203], v[106:109]
	v_mfma_f32_16x16x32_bf16 v[102:105], v[146:149], v[196:199], v[102:105]
	v_mfma_f32_16x16x32_bf16 v[102:105], v[150:153], v[200:203], v[102:105]
	v_mfma_f32_16x16x32_bf16 v[98:101], v[174:177], v[196:199], v[98:101]
	v_mfma_f32_16x16x32_bf16 v[98:101], v[178:181], v[200:203], v[98:101]
	v_mfma_f32_16x16x32_bf16 v[94:97], v[130:133], v[204:207], v[94:97]
	v_mfma_f32_16x16x32_bf16 v[94:97], v[134:137], v[208:211], v[94:97]
	v_mfma_f32_16x16x32_bf16 v[90:93], v[138:141], v[204:207], v[90:93]
	v_mfma_f32_16x16x32_bf16 v[90:93], v[142:145], v[208:211], v[90:93]
	v_mfma_f32_16x16x32_bf16 v[86:89], v[146:149], v[204:207], v[86:89]
	v_mfma_f32_16x16x32_bf16 v[86:89], v[150:153], v[208:211], v[86:89]
	v_mfma_f32_16x16x32_bf16 v[82:85], v[174:177], v[204:207], v[82:85]
	v_mfma_f32_16x16x32_bf16 v[82:85], v[178:181], v[208:211], v[82:85]
	v_mfma_f32_16x16x32_bf16 v[78:81], v[130:133], v[212:215], v[78:81]
	v_mfma_f32_16x16x32_bf16 v[78:81], v[134:137], v[216:219], v[78:81]
	v_mfma_f32_16x16x32_bf16 v[74:77], v[138:141], v[212:215], v[74:77]
	v_mfma_f32_16x16x32_bf16 v[74:77], v[142:145], v[216:219], v[74:77]
	v_mfma_f32_16x16x32_bf16 v[70:73], v[146:149], v[212:215], v[70:73]
	v_mfma_f32_16x16x32_bf16 v[70:73], v[150:153], v[216:219], v[70:73]
	v_mfma_f32_16x16x32_bf16 v[66:69], v[174:177], v[212:215], v[66:69]
	v_mfma_f32_16x16x32_bf16 v[66:69], v[178:181], v[216:219], v[66:69]
	s_setprio 0
	s_barrier
	s_add_i32 s74, s67, s3
	s_add_u32 s98, s48, 0x80
	s_addc_u32 s99, s49, 0
	s_mov_b32 m0, s74
	ds_read_b128 v[184:187], v189 offset:16384
	ds_read_b128 v[192:195], v189 offset:17408
	ds_read_b128 v[196:199], v189 offset:18432
	ds_read_b128 v[200:203], v189 offset:19456
	ds_read_b128 v[204:207], v189 offset:20480
	ds_read_b128 v[208:211], v189 offset:21504
	ds_read_b128 v[212:215], v189 offset:22528
	ds_read_b128 v[216:219], v189 offset:23552
	global_load_lds_dwordx4 v156, s[48:49]
	s_add_i32 m0, s74, 0x2000
	s_add_u32 s74, s48, 0x100000
	s_addc_u32 s75, s49, 0
	s_add_i32 s76, s68, s3
	global_load_lds_dwordx4 v160, s[48:49]
	s_mov_b32 m0, s76
	global_load_lds_dwordx4 v156, s[74:75]
	s_add_i32 m0, s76, 0x2000
	s_nop 0
	global_load_lds_dwordx4 v160, s[74:75]
	s_add_u32 s100, s50, 0x80
	s_addc_u32 s101, s51, 0
	s_mov_b32 m0, s13
	s_nop 0
	global_load_lds_dwordx4 v154, s[50:51]
	s_mov_b32 m0, s21
	s_nop 0
	global_load_lds_dwordx4 v158, s[50:51]
	s_waitcnt vmcnt(8)
	s_waitcnt lgkmcnt(0)
	s_barrier
	s_setprio 1
	v_mfma_f32_16x16x32_bf16 v[62:65], v[130:133], v[184:187], v[62:65]
	v_mfma_f32_16x16x32_bf16 v[62:65], v[134:137], v[192:195], v[62:65]
	v_mfma_f32_16x16x32_bf16 v[58:61], v[138:141], v[184:187], v[58:61]
	v_mfma_f32_16x16x32_bf16 v[58:61], v[142:145], v[192:195], v[58:61]
	v_mfma_f32_16x16x32_bf16 v[54:57], v[146:149], v[184:187], v[54:57]
	v_mfma_f32_16x16x32_bf16 v[54:57], v[150:153], v[192:195], v[54:57]
	v_mfma_f32_16x16x32_bf16 v[50:53], v[174:177], v[184:187], v[50:53]
	v_mfma_f32_16x16x32_bf16 v[50:53], v[178:181], v[192:195], v[50:53]
	v_mfma_f32_16x16x32_bf16 v[46:49], v[130:133], v[196:199], v[46:49]
	v_mfma_f32_16x16x32_bf16 v[46:49], v[134:137], v[200:203], v[46:49]
	v_mfma_f32_16x16x32_bf16 v[42:45], v[138:141], v[196:199], v[42:45]
	v_mfma_f32_16x16x32_bf16 v[42:45], v[142:145], v[200:203], v[42:45]
	v_mfma_f32_16x16x32_bf16 v[38:41], v[146:149], v[196:199], v[38:41]
	v_mfma_f32_16x16x32_bf16 v[38:41], v[150:153], v[200:203], v[38:41]
	v_mfma_f32_16x16x32_bf16 v[34:37], v[174:177], v[196:199], v[34:37]
	v_mfma_f32_16x16x32_bf16 v[34:37], v[178:181], v[200:203], v[34:37]
	v_mfma_f32_16x16x32_bf16 v[30:33], v[130:133], v[204:207], v[30:33]
	v_mfma_f32_16x16x32_bf16 v[30:33], v[134:137], v[208:211], v[30:33]
	v_mfma_f32_16x16x32_bf16 v[26:29], v[138:141], v[204:207], v[26:29]
	v_mfma_f32_16x16x32_bf16 v[26:29], v[142:145], v[208:211], v[26:29]
	v_mfma_f32_16x16x32_bf16 v[22:25], v[146:149], v[204:207], v[22:25]
	v_mfma_f32_16x16x32_bf16 v[22:25], v[150:153], v[208:211], v[22:25]
	v_mfma_f32_16x16x32_bf16 v[18:21], v[174:177], v[204:207], v[18:21]
	v_mfma_f32_16x16x32_bf16 v[18:21], v[178:181], v[208:211], v[18:21]
	v_mfma_f32_16x16x32_bf16 v[14:17], v[130:133], v[212:215], v[14:17]
	v_mfma_f32_16x16x32_bf16 v[14:17], v[134:137], v[216:219], v[14:17]
	v_mfma_f32_16x16x32_bf16 v[10:13], v[138:141], v[212:215], v[10:13]
	v_mfma_f32_16x16x32_bf16 v[10:13], v[142:145], v[216:219], v[10:13]
	v_mfma_f32_16x16x32_bf16 v[6:9], v[146:149], v[212:215], v[6:9]
	v_mfma_f32_16x16x32_bf16 v[6:9], v[150:153], v[216:219], v[6:9]
	v_mfma_f32_16x16x32_bf16 v[2:5], v[174:177], v[212:215], v[2:5]
	v_mfma_f32_16x16x32_bf16 v[2:5], v[178:181], v[216:219], v[2:5]
	s_setprio 0
	s_barrier
	s_add_i32 s74, 0, 0x18000
	s_add_i32 s75, 0, 0x1c000
	v_add_u32_e32 v142, s74, v1
	v_add_u32_e32 v178, s75, v1
	ds_read_b128 v[130:133], v142
	ds_read_b128 v[134:137], v142 offset:1024
	ds_read_b128 v[138:141], v142 offset:2048
	ds_read_b128 v[142:145], v142 offset:3072
	ds_read_b128 v[146:149], v178
	ds_read_b128 v[150:153], v178 offset:1024
	ds_read_b128 v[174:177], v178 offset:2048
	ds_read_b128 v[178:181], v178 offset:3072
	s_add_u32 s50, s50, 0x100000
	s_addc_u32 s51, s51, 0
	s_mov_b32 m0, s33
	ds_read_b128 v[184:187], v189 offset:32768
	ds_read_b128 v[192:195], v189 offset:33792
	ds_read_b128 v[196:199], v189 offset:34816
	ds_read_b128 v[200:203], v189 offset:35840
	ds_read_b128 v[204:207], v189 offset:36864
	ds_read_b128 v[208:211], v189 offset:37888
	ds_read_b128 v[212:215], v189 offset:38912
	ds_read_b128 v[216:219], v189 offset:39936
	global_load_lds_dwordx4 v154, s[50:51]
	s_mov_b32 m0, s35
	s_nop 0
	global_load_lds_dwordx4 v158, s[50:51]
	s_waitcnt vmcnt(8)
	s_waitcnt lgkmcnt(0)
	s_barrier
	s_setprio 1
	v_mfma_f32_16x16x32_bf16 v[126:129], v[130:133], v[184:187], v[126:129]
	v_mfma_f32_16x16x32_bf16 v[126:129], v[134:137], v[192:195], v[126:129]
	v_mfma_f32_16x16x32_bf16 v[122:125], v[138:141], v[184:187], v[122:125]
	v_mfma_f32_16x16x32_bf16 v[122:125], v[142:145], v[192:195], v[122:125]
	v_mfma_f32_16x16x32_bf16 v[118:121], v[146:149], v[184:187], v[118:121]
	v_mfma_f32_16x16x32_bf16 v[118:121], v[150:153], v[192:195], v[118:121]
	v_mfma_f32_16x16x32_bf16 v[114:117], v[174:177], v[184:187], v[114:117]
	v_mfma_f32_16x16x32_bf16 v[114:117], v[178:181], v[192:195], v[114:117]
	v_mfma_f32_16x16x32_bf16 v[110:113], v[130:133], v[196:199], v[110:113]
	v_mfma_f32_16x16x32_bf16 v[110:113], v[134:137], v[200:203], v[110:113]
	v_mfma_f32_16x16x32_bf16 v[106:109], v[138:141], v[196:199], v[106:109]
	v_mfma_f32_16x16x32_bf16 v[106:109], v[142:145], v[200:203], v[106:109]
	v_mfma_f32_16x16x32_bf16 v[102:105], v[146:149], v[196:199], v[102:105]
	v_mfma_f32_16x16x32_bf16 v[102:105], v[150:153], v[200:203], v[102:105]
	v_mfma_f32_16x16x32_bf16 v[98:101], v[174:177], v[196:199], v[98:101]
	v_mfma_f32_16x16x32_bf16 v[98:101], v[178:181], v[200:203], v[98:101]
	v_mfma_f32_16x16x32_bf16 v[94:97], v[130:133], v[204:207], v[94:97]
	v_mfma_f32_16x16x32_bf16 v[94:97], v[134:137], v[208:211], v[94:97]
	v_mfma_f32_16x16x32_bf16 v[90:93], v[138:141], v[204:207], v[90:93]
	v_mfma_f32_16x16x32_bf16 v[90:93], v[142:145], v[208:211], v[90:93]
	v_mfma_f32_16x16x32_bf16 v[86:89], v[146:149], v[204:207], v[86:89]
	v_mfma_f32_16x16x32_bf16 v[86:89], v[150:153], v[208:211], v[86:89]
	v_mfma_f32_16x16x32_bf16 v[82:85], v[174:177], v[204:207], v[82:85]
	v_mfma_f32_16x16x32_bf16 v[82:85], v[178:181], v[208:211], v[82:85]
	v_mfma_f32_16x16x32_bf16 v[78:81], v[130:133], v[212:215], v[78:81]
	v_mfma_f32_16x16x32_bf16 v[78:81], v[134:137], v[216:219], v[78:81]
	v_mfma_f32_16x16x32_bf16 v[74:77], v[138:141], v[212:215], v[74:77]
	v_mfma_f32_16x16x32_bf16 v[74:77], v[142:145], v[216:219], v[74:77]
	v_mfma_f32_16x16x32_bf16 v[70:73], v[146:149], v[212:215], v[70:73]
	v_mfma_f32_16x16x32_bf16 v[70:73], v[150:153], v[216:219], v[70:73]
	v_mfma_f32_16x16x32_bf16 v[66:69], v[174:177], v[212:215], v[66:69]
	v_mfma_f32_16x16x32_bf16 v[66:69], v[178:181], v[216:219], v[66:69]
	s_setprio 0
	s_barrier
	s_add_i32 s50, s74, s3
	s_mov_b32 m0, s50
	ds_read_b128 v[184:187], v189 offset:49152
	ds_read_b128 v[192:195], v189 offset:50176
	ds_read_b128 v[196:199], v189 offset:51200
	ds_read_b128 v[200:203], v189 offset:52224
	ds_read_b128 v[204:207], v189 offset:53248
	ds_read_b128 v[208:211], v189 offset:54272
	ds_read_b128 v[212:215], v189 offset:55296
	ds_read_b128 v[216:219], v189 offset:56320
	global_load_lds_dwordx4 v156, s[98:99]
	s_add_i32 m0, s50, 0x2000
	s_add_u32 s48, s48, 0x100080
	s_addc_u32 s49, s49, 0
	s_add_i32 s50, s75, s3
	global_load_lds_dwordx4 v160, s[98:99]
	s_mov_b32 m0, s50
	s_nop 0
	global_load_lds_dwordx4 v156, s[48:49]
	s_add_i32 m0, s50, 0x2000
	s_nop 0
	global_load_lds_dwordx4 v160, s[48:49]
	s_mov_b32 m0, s62
	s_nop 0
	global_load_lds_dwordx4 v154, s[100:101]
	s_mov_b32 m0, s63
	s_nop 0
	global_load_lds_dwordx4 v158, s[100:101]
	s_waitcnt vmcnt(8)
	s_waitcnt lgkmcnt(0)
	s_barrier
	s_setprio 1
	v_mfma_f32_16x16x32_bf16 v[62:65], v[130:133], v[184:187], v[62:65]
	v_mfma_f32_16x16x32_bf16 v[62:65], v[134:137], v[192:195], v[62:65]
	v_mfma_f32_16x16x32_bf16 v[58:61], v[138:141], v[184:187], v[58:61]
	v_mfma_f32_16x16x32_bf16 v[58:61], v[142:145], v[192:195], v[58:61]
	v_mfma_f32_16x16x32_bf16 v[54:57], v[146:149], v[184:187], v[54:57]
	v_mfma_f32_16x16x32_bf16 v[54:57], v[150:153], v[192:195], v[54:57]
	v_mfma_f32_16x16x32_bf16 v[50:53], v[174:177], v[184:187], v[50:53]
	v_mfma_f32_16x16x32_bf16 v[50:53], v[178:181], v[192:195], v[50:53]
	v_mfma_f32_16x16x32_bf16 v[46:49], v[130:133], v[196:199], v[46:49]
	v_mfma_f32_16x16x32_bf16 v[46:49], v[134:137], v[200:203], v[46:49]
	v_mfma_f32_16x16x32_bf16 v[42:45], v[138:141], v[196:199], v[42:45]
	v_mfma_f32_16x16x32_bf16 v[42:45], v[142:145], v[200:203], v[42:45]
	v_mfma_f32_16x16x32_bf16 v[38:41], v[146:149], v[196:199], v[38:41]
	v_mfma_f32_16x16x32_bf16 v[38:41], v[150:153], v[200:203], v[38:41]
	v_mfma_f32_16x16x32_bf16 v[34:37], v[174:177], v[196:199], v[34:37]
	v_mfma_f32_16x16x32_bf16 v[34:37], v[178:181], v[200:203], v[34:37]
	v_mfma_f32_16x16x32_bf16 v[30:33], v[130:133], v[204:207], v[30:33]
	v_mfma_f32_16x16x32_bf16 v[30:33], v[134:137], v[208:211], v[30:33]
	v_mfma_f32_16x16x32_bf16 v[26:29], v[138:141], v[204:207], v[26:29]
	v_mfma_f32_16x16x32_bf16 v[26:29], v[142:145], v[208:211], v[26:29]
	v_mfma_f32_16x16x32_bf16 v[22:25], v[146:149], v[204:207], v[22:25]
	v_mfma_f32_16x16x32_bf16 v[22:25], v[150:153], v[208:211], v[22:25]
	v_mfma_f32_16x16x32_bf16 v[18:21], v[174:177], v[204:207], v[18:21]
	v_mfma_f32_16x16x32_bf16 v[18:21], v[178:181], v[208:211], v[18:21]
	v_mfma_f32_16x16x32_bf16 v[14:17], v[130:133], v[212:215], v[14:17]
	v_mfma_f32_16x16x32_bf16 v[14:17], v[134:137], v[216:219], v[14:17]
	v_mfma_f32_16x16x32_bf16 v[10:13], v[138:141], v[212:215], v[10:13]
	v_mfma_f32_16x16x32_bf16 v[10:13], v[142:145], v[216:219], v[10:13]
	v_mfma_f32_16x16x32_bf16 v[6:9], v[146:149], v[212:215], v[6:9]
	v_mfma_f32_16x16x32_bf16 v[6:9], v[150:153], v[216:219], v[6:9]
	v_mfma_f32_16x16x32_bf16 v[2:5], v[174:177], v[212:215], v[2:5]
	v_mfma_f32_16x16x32_bf16 v[2:5], v[178:181], v[216:219], v[2:5]
	s_setprio 0
	s_barrier
	s_add_i32 s73, s73, 2
	s_add_u32 s46, s46, 0x100
	s_addc_u32 s47, s47, 0
	s_add_u32 s71, s71, 0x100
	s_addc_u32 s72, s72, 0
	s_cmp_gt_u32 s73, 61
	s_cbranch_scc0 .LBB0_2635
	s_and_b64 vcc, exec, s[36:37]
	s_cbranch_vccz .LBB0_2638
	s_barrier

.LBB0_2720:
	ds_read_b128 v[148:151], v159
	ds_read_b128 v[164:167], v159 offset:1024
	ds_read_b128 v[168:171], v159 offset:2048
	ds_read_b128 v[172:175], v159 offset:3072
	ds_read_b128 v[176:179], v160
	ds_read_b128 v[184:187], v160 offset:1024
	ds_read_b128 v[188:191], v160 offset:2048
	ds_read_b128 v[192:195], v160 offset:3072
	s_add_u32 s40, s6, 0xfff00080
	s_addc_u32 s41, s7, -1
	s_cmp_eq_u32 s82, 60
	s_cselect_b32 s43, s29, s41
	s_cselect_b32 s42, s78, s40
	s_cselect_b32 s41, s27, s81
	s_cselect_b32 s40, s79, s80
	s_add_i32 m0, s44, 0xc000
	ds_read_b128 v[196:199], v161
	ds_read_b128 v[200:203], v161 offset:1024
	ds_read_b128 v[204:207], v161 offset:2048
	ds_read_b128 v[208:211], v161 offset:3072
	ds_read_b128 v[212:215], v161 offset:4096
	ds_read_b128 v[216:219], v161 offset:5120
	ds_read_b128 v[220:223], v161 offset:6144
	ds_read_b128 v[224:227], v161 offset:7168
	global_load_lds_dwordx4 v140, s[6:7]
	s_add_i32 m0, s44, 0xe000
	s_nop 0
	global_load_lds_dwordx4 v142, s[6:7]
	s_waitcnt vmcnt(8)
	s_waitcnt lgkmcnt(0)
	s_barrier
	s_setprio 1
	v_mfma_f32_16x16x32_bf16 v[126:129], v[148:151], v[196:199], v[126:129]
	v_mfma_f32_16x16x32_bf16 v[126:129], v[164:167], v[200:203], v[126:129]
	v_mfma_f32_16x16x32_bf16 v[118:121], v[168:171], v[196:199], v[118:121]
	v_mfma_f32_16x16x32_bf16 v[118:121], v[172:175], v[200:203], v[118:121]
	v_mfma_f32_16x16x32_bf16 v[122:125], v[176:179], v[196:199], v[122:125]
	v_mfma_f32_16x16x32_bf16 v[122:125], v[184:187], v[200:203], v[122:125]
	v_mfma_f32_16x16x32_bf16 v[114:117], v[188:191], v[196:199], v[114:117]
	v_mfma_f32_16x16x32_bf16 v[114:117], v[192:195], v[200:203], v[114:117]
	v_mfma_f32_16x16x32_bf16 v[110:113], v[148:151], v[204:207], v[110:113]
	v_mfma_f32_16x16x32_bf16 v[110:113], v[164:167], v[208:211], v[110:113]
	v_mfma_f32_16x16x32_bf16 v[102:105], v[168:171], v[204:207], v[102:105]
	v_mfma_f32_16x16x32_bf16 v[102:105], v[172:175], v[208:211], v[102:105]
	v_mfma_f32_16x16x32_bf16 v[106:109], v[176:179], v[204:207], v[106:109]
	v_mfma_f32_16x16x32_bf16 v[106:109], v[184:187], v[208:211], v[106:109]
	v_mfma_f32_16x16x32_bf16 v[98:101], v[188:191], v[204:207], v[98:101]
	v_mfma_f32_16x16x32_bf16 v[98:101], v[192:195], v[208:211], v[98:101]
	v_mfma_f32_16x16x32_bf16 v[94:97], v[148:151], v[212:215], v[94:97]
	v_mfma_f32_16x16x32_bf16 v[94:97], v[164:167], v[216:219], v[94:97]
	v_mfma_f32_16x16x32_bf16 v[86:89], v[168:171], v[212:215], v[86:89]
	v_mfma_f32_16x16x32_bf16 v[86:89], v[172:175], v[216:219], v[86:89]
	v_mfma_f32_16x16x32_bf16 v[90:93], v[176:179], v[212:215], v[90:93]
	v_mfma_f32_16x16x32_bf16 v[90:93], v[184:187], v[216:219], v[90:93]
	v_mfma_f32_16x16x32_bf16 v[82:85], v[188:191], v[212:215], v[82:85]
	v_mfma_f32_16x16x32_bf16 v[82:85], v[192:195], v[216:219], v[82:85]
	v_mfma_f32_16x16x32_bf16 v[78:81], v[148:151], v[220:223], v[78:81]
	v_mfma_f32_16x16x32_bf16 v[78:81], v[164:167], v[224:227], v[78:81]
	v_mfma_f32_16x16x32_bf16 v[70:73], v[168:171], v[220:223], v[70:73]
	v_mfma_f32_16x16x32_bf16 v[70:73], v[172:175], v[224:227], v[70:73]
	v_mfma_f32_16x16x32_bf16 v[74:77], v[176:179], v[220:223], v[74:77]
	v_mfma_f32_16x16x32_bf16 v[74:77], v[184:187], v[224:227], v[74:77]
	v_mfma_f32_16x16x32_bf16 v[66:69], v[188:191], v[220:223], v[66:69]
	v_mfma_f32_16x16x32_bf16 v[66:69], v[192:195], v[224:227], v[66:69]
	s_setprio 0
	s_barrier
	s_add_i32 s83, s68, s13
	s_add_u32 s98, s40, 0x80
	s_addc_u32 s99, s41, 0
	s_mov_b32 m0, s83
	ds_read_b128 v[196:199], v161 offset:16384
	ds_read_b128 v[200:203], v161 offset:17408
	ds_read_b128 v[204:207], v161 offset:18432
	ds_read_b128 v[208:211], v161 offset:19456
	ds_read_b128 v[212:215], v161 offset:20480
	ds_read_b128 v[216:219], v161 offset:21504
	ds_read_b128 v[220:223], v161 offset:22528
	ds_read_b128 v[224:227], v161 offset:23552
	global_load_lds_dwordx4 v132, s[40:41]
	s_add_i32 m0, s83, 0x2000
	s_add_u32 s84, s40, 0x100000
	s_addc_u32 s85, s41, 0
	s_add_i32 s83, s69, s13
	global_load_lds_dwordx4 v136, s[40:41]
	s_mov_b32 m0, s83
	global_load_lds_dwordx4 v132, s[84:85]
	s_add_i32 m0, s83, 0x2000
	s_nop 0
	global_load_lds_dwordx4 v136, s[84:85]
	s_add_u32 s100, s42, 0x80
	s_addc_u32 s101, s43, 0
	s_mov_b32 m0, s44
	s_nop 0
	global_load_lds_dwordx4 v130, s[42:43]
	s_mov_b32 m0, s45
	s_nop 0
	global_load_lds_dwordx4 v134, s[42:43]
	s_waitcnt vmcnt(8)
	s_waitcnt lgkmcnt(0)
	s_barrier
	s_setprio 1
	v_mfma_f32_16x16x32_bf16 v[62:65], v[148:151], v[196:199], v[62:65]
	v_mfma_f32_16x16x32_bf16 v[62:65], v[164:167], v[200:203], v[62:65]
	v_mfma_f32_16x16x32_bf16 v[54:57], v[168:171], v[196:199], v[54:57]
	v_mfma_f32_16x16x32_bf16 v[54:57], v[172:175], v[200:203], v[54:57]
	v_mfma_f32_16x16x32_bf16 v[58:61], v[176:179], v[196:199], v[58:61]
	v_mfma_f32_16x16x32_bf16 v[58:61], v[184:187], v[200:203], v[58:61]
	v_mfma_f32_16x16x32_bf16 v[50:53], v[188:191], v[196:199], v[50:53]
	v_mfma_f32_16x16x32_bf16 v[50:53], v[192:195], v[200:203], v[50:53]
	v_mfma_f32_16x16x32_bf16 v[46:49], v[148:151], v[204:207], v[46:49]
	v_mfma_f32_16x16x32_bf16 v[46:49], v[164:167], v[208:211], v[46:49]
	v_mfma_f32_16x16x32_bf16 v[38:41], v[168:171], v[204:207], v[38:41]
	v_mfma_f32_16x16x32_bf16 v[38:41], v[172:175], v[208:211], v[38:41]
	v_mfma_f32_16x16x32_bf16 v[42:45], v[176:179], v[204:207], v[42:45]
	v_mfma_f32_16x16x32_bf16 v[42:45], v[184:187], v[208:211], v[42:45]
	v_mfma_f32_16x16x32_bf16 v[34:37], v[188:191], v[204:207], v[34:37]
	v_mfma_f32_16x16x32_bf16 v[34:37], v[192:195], v[208:211], v[34:37]
	v_mfma_f32_16x16x32_bf16 v[30:33], v[148:151], v[212:215], v[30:33]
	v_mfma_f32_16x16x32_bf16 v[30:33], v[164:167], v[216:219], v[30:33]
	v_mfma_f32_16x16x32_bf16 v[22:25], v[168:171], v[212:215], v[22:25]
	v_mfma_f32_16x16x32_bf16 v[22:25], v[172:175], v[216:219], v[22:25]
	v_mfma_f32_16x16x32_bf16 v[26:29], v[176:179], v[212:215], v[26:29]
	v_mfma_f32_16x16x32_bf16 v[26:29], v[184:187], v[216:219], v[26:29]
	v_mfma_f32_16x16x32_bf16 v[18:21], v[188:191], v[212:215], v[18:21]
	v_mfma_f32_16x16x32_bf16 v[18:21], v[192:195], v[216:219], v[18:21]
	v_mfma_f32_16x16x32_bf16 v[14:17], v[148:151], v[220:223], v[14:17]
	v_mfma_f32_16x16x32_bf16 v[14:17], v[164:167], v[224:227], v[14:17]
	v_mfma_f32_16x16x32_bf16 v[6:9], v[168:171], v[220:223], v[6:9]
	v_mfma_f32_16x16x32_bf16 v[6:9], v[172:175], v[224:227], v[6:9]
	v_mfma_f32_16x16x32_bf16 v[10:13], v[176:179], v[220:223], v[10:13]
	v_mfma_f32_16x16x32_bf16 v[10:13], v[184:187], v[224:227], v[10:13]
	v_mfma_f32_16x16x32_bf16 v[2:5], v[188:191], v[220:223], v[2:5]
	v_mfma_f32_16x16x32_bf16 v[2:5], v[192:195], v[224:227], v[2:5]
	s_setprio 0
	s_barrier
	s_add_i32 s83, 0, 0x18000
	v_add_u32_e32 v138, s83, v155
	s_add_i32 s84, 0, 0x1c000
	ds_read_b128 v[148:151], v138
	ds_read_b128 v[164:167], v138 offset:1024
	ds_read_b128 v[168:171], v138 offset:2048
	ds_read_b128 v[172:175], v138 offset:3072
	v_add_u32_e32 v138, s84, v155
	ds_read_b128 v[176:179], v138
	ds_read_b128 v[184:187], v138 offset:1024
	ds_read_b128 v[188:191], v138 offset:2048
	ds_read_b128 v[192:195], v138 offset:3072
	s_add_u32 s42, s42, 0x100000
	s_addc_u32 s43, s43, 0
	s_mov_b32 m0, s46
	ds_read_b128 v[196:199], v161 offset:32768
	ds_read_b128 v[200:203], v161 offset:33792
	ds_read_b128 v[204:207], v161 offset:34816
	ds_read_b128 v[208:211], v161 offset:35840
	ds_read_b128 v[212:215], v161 offset:36864
	ds_read_b128 v[216:219], v161 offset:37888
	ds_read_b128 v[220:223], v161 offset:38912
	ds_read_b128 v[224:227], v161 offset:39936
	global_load_lds_dwordx4 v130, s[42:43]
	s_mov_b32 m0, s47
	s_nop 0
	global_load_lds_dwordx4 v134, s[42:43]
	s_waitcnt vmcnt(8)
	s_waitcnt lgkmcnt(0)
	s_barrier
	s_setprio 1
	v_mfma_f32_16x16x32_bf16 v[126:129], v[148:151], v[196:199], v[126:129]
	v_mfma_f32_16x16x32_bf16 v[126:129], v[164:167], v[200:203], v[126:129]
	v_mfma_f32_16x16x32_bf16 v[118:121], v[168:171], v[196:199], v[118:121]
	v_mfma_f32_16x16x32_bf16 v[118:121], v[172:175], v[200:203], v[118:121]
	v_mfma_f32_16x16x32_bf16 v[122:125], v[176:179], v[196:199], v[122:125]
	v_mfma_f32_16x16x32_bf16 v[122:125], v[184:187], v[200:203], v[122:125]
	v_mfma_f32_16x16x32_bf16 v[114:117], v[188:191], v[196:199], v[114:117]
	v_mfma_f32_16x16x32_bf16 v[114:117], v[192:195], v[200:203], v[114:117]
	v_mfma_f32_16x16x32_bf16 v[110:113], v[148:151], v[204:207], v[110:113]
	v_mfma_f32_16x16x32_bf16 v[110:113], v[164:167], v[208:211], v[110:113]
	v_mfma_f32_16x16x32_bf16 v[102:105], v[168:171], v[204:207], v[102:105]
	v_mfma_f32_16x16x32_bf16 v[102:105], v[172:175], v[208:211], v[102:105]
	v_mfma_f32_16x16x32_bf16 v[106:109], v[176:179], v[204:207], v[106:109]
	v_mfma_f32_16x16x32_bf16 v[106:109], v[184:187], v[208:211], v[106:109]
	v_mfma_f32_16x16x32_bf16 v[98:101], v[188:191], v[204:207], v[98:101]
	v_mfma_f32_16x16x32_bf16 v[98:101], v[192:195], v[208:211], v[98:101]
	v_mfma_f32_16x16x32_bf16 v[94:97], v[148:151], v[212:215], v[94:97]
	v_mfma_f32_16x16x32_bf16 v[94:97], v[164:167], v[216:219], v[94:97]
	v_mfma_f32_16x16x32_bf16 v[86:89], v[168:171], v[212:215], v[86:89]
	v_mfma_f32_16x16x32_bf16 v[86:89], v[172:175], v[216:219], v[86:89]
	v_mfma_f32_16x16x32_bf16 v[90:93], v[176:179], v[212:215], v[90:93]
	v_mfma_f32_16x16x32_bf16 v[90:93], v[184:187], v[216:219], v[90:93]
	v_mfma_f32_16x16x32_bf16 v[82:85], v[188:191], v[212:215], v[82:85]
	v_mfma_f32_16x16x32_bf16 v[82:85], v[192:195], v[216:219], v[82:85]
	v_mfma_f32_16x16x32_bf16 v[78:81], v[148:151], v[220:223], v[78:81]
	v_mfma_f32_16x16x32_bf16 v[78:81], v[164:167], v[224:227], v[78:81]
	v_mfma_f32_16x16x32_bf16 v[70:73], v[168:171], v[220:223], v[70:73]
	v_mfma_f32_16x16x32_bf16 v[70:73], v[172:175], v[224:227], v[70:73]
	v_mfma_f32_16x16x32_bf16 v[74:77], v[176:179], v[220:223], v[74:77]
	v_mfma_f32_16x16x32_bf16 v[74:77], v[184:187], v[224:227], v[74:77]
	v_mfma_f32_16x16x32_bf16 v[66:69], v[188:191], v[220:223], v[66:69]
	v_mfma_f32_16x16x32_bf16 v[66:69], v[192:195], v[224:227], v[66:69]
	s_setprio 0
	s_barrier
	s_add_i32 s42, s83, s13
	s_mov_b32 m0, s42
	ds_read_b128 v[196:199], v161 offset:49152
	ds_read_b128 v[200:203], v161 offset:50176
	ds_read_b128 v[204:207], v161 offset:51200
	ds_read_b128 v[208:211], v161 offset:52224
	ds_read_b128 v[212:215], v161 offset:53248
	ds_read_b128 v[216:219], v161 offset:54272
	ds_read_b128 v[220:223], v161 offset:55296
	ds_read_b128 v[224:227], v161 offset:56320
	global_load_lds_dwordx4 v132, s[98:99]
	s_add_i32 m0, s42, 0x2000
	s_add_u32 s40, s40, 0x100080
	s_addc_u32 s41, s41, 0
	s_add_i32 s42, s84, s13
	global_load_lds_dwordx4 v136, s[98:99]
	s_mov_b32 m0, s42
	s_nop 0
	global_load_lds_dwordx4 v132, s[40:41]
	s_add_i32 m0, s42, 0x2000
	s_nop 0
	global_load_lds_dwordx4 v136, s[40:41]
	s_mov_b32 m0, s59
	s_nop 0
	global_load_lds_dwordx4 v130, s[100:101]
	s_mov_b32 m0, s62
	s_nop 0
	global_load_lds_dwordx4 v134, s[100:101]
	s_waitcnt vmcnt(8)
	s_waitcnt lgkmcnt(0)
	s_barrier
	s_setprio 1
	v_mfma_f32_16x16x32_bf16 v[62:65], v[148:151], v[196:199], v[62:65]
	v_mfma_f32_16x16x32_bf16 v[62:65], v[164:167], v[200:203], v[62:65]
	v_mfma_f32_16x16x32_bf16 v[54:57], v[168:171], v[196:199], v[54:57]
	v_mfma_f32_16x16x32_bf16 v[54:57], v[172:175], v[200:203], v[54:57]
	v_mfma_f32_16x16x32_bf16 v[58:61], v[176:179], v[196:199], v[58:61]
	v_mfma_f32_16x16x32_bf16 v[58:61], v[184:187], v[200:203], v[58:61]
	v_mfma_f32_16x16x32_bf16 v[50:53], v[188:191], v[196:199], v[50:53]
	v_mfma_f32_16x16x32_bf16 v[50:53], v[192:195], v[200:203], v[50:53]
	v_mfma_f32_16x16x32_bf16 v[46:49], v[148:151], v[204:207], v[46:49]
	v_mfma_f32_16x16x32_bf16 v[46:49], v[164:167], v[208:211], v[46:49]
	v_mfma_f32_16x16x32_bf16 v[38:41], v[168:171], v[204:207], v[38:41]
	v_mfma_f32_16x16x32_bf16 v[38:41], v[172:175], v[208:211], v[38:41]
	v_mfma_f32_16x16x32_bf16 v[42:45], v[176:179], v[204:207], v[42:45]
	v_mfma_f32_16x16x32_bf16 v[42:45], v[184:187], v[208:211], v[42:45]
	v_mfma_f32_16x16x32_bf16 v[34:37], v[188:191], v[204:207], v[34:37]
	v_mfma_f32_16x16x32_bf16 v[34:37], v[192:195], v[208:211], v[34:37]
	v_mfma_f32_16x16x32_bf16 v[30:33], v[148:151], v[212:215], v[30:33]
	v_mfma_f32_16x16x32_bf16 v[30:33], v[164:167], v[216:219], v[30:33]
	v_mfma_f32_16x16x32_bf16 v[22:25], v[168:171], v[212:215], v[22:25]
	v_mfma_f32_16x16x32_bf16 v[22:25], v[172:175], v[216:219], v[22:25]
	v_mfma_f32_16x16x32_bf16 v[26:29], v[176:179], v[212:215], v[26:29]
	v_mfma_f32_16x16x32_bf16 v[26:29], v[184:187], v[216:219], v[26:29]
	v_mfma_f32_16x16x32_bf16 v[18:21], v[188:191], v[212:215], v[18:21]
	v_mfma_f32_16x16x32_bf16 v[18:21], v[192:195], v[216:219], v[18:21]
	v_mfma_f32_16x16x32_bf16 v[14:17], v[148:151], v[220:223], v[14:17]
	v_mfma_f32_16x16x32_bf16 v[14:17], v[164:167], v[224:227], v[14:17]
	v_mfma_f32_16x16x32_bf16 v[6:9], v[168:171], v[220:223], v[6:9]
	v_mfma_f32_16x16x32_bf16 v[6:9], v[172:175], v[224:227], v[6:9]
	v_mfma_f32_16x16x32_bf16 v[10:13], v[176:179], v[220:223], v[10:13]
	v_mfma_f32_16x16x32_bf16 v[10:13], v[184:187], v[224:227], v[10:13]
	v_mfma_f32_16x16x32_bf16 v[2:5], v[188:191], v[220:223], v[2:5]
	v_mfma_f32_16x16x32_bf16 v[2:5], v[192:195], v[224:227], v[2:5]
	s_setprio 0
	s_barrier
	s_add_i32 s82, s82, 2
	s_add_u32 s6, s6, 0x100
	s_addc_u32 s7, s7, 0
	s_add_u32 s80, s80, 0x100
	s_addc_u32 s81, s81, 0
	s_cmp_gt_u32 s82, 61
	s_cbranch_scc0 .LBB0_2720
	s_and_b64 vcc, exec, s[24:25]
	s_cbranch_vccz .LBB0_2723
	s_barrier

.LBB0_2805:
	ds_read_b128 v[130:133], v163
	ds_read_b128 v[134:137], v163 offset:1024
	ds_read_b128 v[138:141], v163 offset:2048
	ds_read_b128 v[142:145], v163 offset:3072
	ds_read_b128 v[146:149], v188
	ds_read_b128 v[150:153], v188 offset:1024
	ds_read_b128 v[174:177], v188 offset:2048
	ds_read_b128 v[178:181], v188 offset:3072
	s_add_u32 s28, s26, 0xffd50080
	s_addc_u32 s29, s27, -1
	s_cmpk_eq_i32 s62, 0xa8
	s_cselect_b32 s37, s7, s29
	s_cselect_b32 s36, s6, s28
	s_cselect_b32 s29, s25, s59
	s_cselect_b32 s28, s24, s12
	s_add_i32 m0, s38, 0xc000
	ds_read_b128 v[184:187], v189
	ds_read_b128 v[192:195], v189 offset:1024
	ds_read_b128 v[196:199], v189 offset:2048
	ds_read_b128 v[200:203], v189 offset:3072
	ds_read_b128 v[204:207], v189 offset:4096
	ds_read_b128 v[208:211], v189 offset:5120
	ds_read_b128 v[212:215], v189 offset:6144
	ds_read_b128 v[216:219], v189 offset:7168
	global_load_lds_dwordx4 v166, s[26:27]
	s_add_i32 m0, s38, 0xe000
	s_nop 0
	global_load_lds_dwordx4 v168, s[26:27]
	s_waitcnt vmcnt(8)
	s_waitcnt lgkmcnt(0)
	s_barrier
	s_setprio 1
	v_mfma_f32_16x16x32_bf16 v[126:129], v[130:133], v[184:187], v[126:129]
	v_mfma_f32_16x16x32_bf16 v[126:129], v[134:137], v[192:195], v[126:129]
	v_mfma_f32_16x16x32_bf16 v[122:125], v[138:141], v[184:187], v[122:125]
	v_mfma_f32_16x16x32_bf16 v[122:125], v[142:145], v[192:195], v[122:125]
	v_mfma_f32_16x16x32_bf16 v[118:121], v[146:149], v[184:187], v[118:121]
	v_mfma_f32_16x16x32_bf16 v[118:121], v[150:153], v[192:195], v[118:121]
	v_mfma_f32_16x16x32_bf16 v[114:117], v[174:177], v[184:187], v[114:117]
	v_mfma_f32_16x16x32_bf16 v[114:117], v[178:181], v[192:195], v[114:117]
	v_mfma_f32_16x16x32_bf16 v[110:113], v[130:133], v[196:199], v[110:113]
	v_mfma_f32_16x16x32_bf16 v[110:113], v[134:137], v[200:203], v[110:113]
	v_mfma_f32_16x16x32_bf16 v[106:109], v[138:141], v[196:199], v[106:109]
	v_mfma_f32_16x16x32_bf16 v[106:109], v[142:145], v[200:203], v[106:109]
	v_mfma_f32_16x16x32_bf16 v[102:105], v[146:149], v[196:199], v[102:105]
	v_mfma_f32_16x16x32_bf16 v[102:105], v[150:153], v[200:203], v[102:105]
	v_mfma_f32_16x16x32_bf16 v[98:101], v[174:177], v[196:199], v[98:101]
	v_mfma_f32_16x16x32_bf16 v[98:101], v[178:181], v[200:203], v[98:101]
	v_mfma_f32_16x16x32_bf16 v[94:97], v[130:133], v[204:207], v[94:97]
	v_mfma_f32_16x16x32_bf16 v[94:97], v[134:137], v[208:211], v[94:97]
	v_mfma_f32_16x16x32_bf16 v[90:93], v[138:141], v[204:207], v[90:93]
	v_mfma_f32_16x16x32_bf16 v[90:93], v[142:145], v[208:211], v[90:93]
	v_mfma_f32_16x16x32_bf16 v[86:89], v[146:149], v[204:207], v[86:89]
	v_mfma_f32_16x16x32_bf16 v[86:89], v[150:153], v[208:211], v[86:89]
	v_mfma_f32_16x16x32_bf16 v[82:85], v[174:177], v[204:207], v[82:85]
	v_mfma_f32_16x16x32_bf16 v[82:85], v[178:181], v[208:211], v[82:85]
	v_mfma_f32_16x16x32_bf16 v[78:81], v[130:133], v[212:215], v[78:81]
	v_mfma_f32_16x16x32_bf16 v[78:81], v[134:137], v[216:219], v[78:81]
	v_mfma_f32_16x16x32_bf16 v[74:77], v[138:141], v[212:215], v[74:77]
	v_mfma_f32_16x16x32_bf16 v[74:77], v[142:145], v[216:219], v[74:77]
	v_mfma_f32_16x16x32_bf16 v[70:73], v[146:149], v[212:215], v[70:73]
	v_mfma_f32_16x16x32_bf16 v[70:73], v[150:153], v[216:219], v[70:73]
	v_mfma_f32_16x16x32_bf16 v[66:69], v[174:177], v[212:215], v[66:69]
	v_mfma_f32_16x16x32_bf16 v[66:69], v[178:181], v[216:219], v[66:69]
	s_setprio 0
	s_barrier
	s_add_i32 s63, s47, s35
	s_add_u32 s98, s28, 0x80
	s_addc_u32 s99, s29, 0
	s_mov_b32 m0, s63
	ds_read_b128 v[184:187], v189 offset:16384
	ds_read_b128 v[192:195], v189 offset:17408
	ds_read_b128 v[196:199], v189 offset:18432
	ds_read_b128 v[200:203], v189 offset:19456
	ds_read_b128 v[204:207], v189 offset:20480
	ds_read_b128 v[208:211], v189 offset:21504
	ds_read_b128 v[212:215], v189 offset:22528
	ds_read_b128 v[216:219], v189 offset:23552
	global_load_lds_dwordx4 v156, s[28:29]
	s_add_i32 m0, s63, 0x2000
	s_add_u32 s66, s28, 0x2b0000
	s_addc_u32 s67, s29, 0
	s_add_i32 s63, s48, s35
	global_load_lds_dwordx4 v160, s[28:29]
	s_mov_b32 m0, s63
	global_load_lds_dwordx4 v156, s[66:67]
	s_add_i32 m0, s63, 0x2000
	s_nop 0
	global_load_lds_dwordx4 v160, s[66:67]
	s_add_u32 s100, s36, 0x80
	s_addc_u32 s101, s37, 0
	s_mov_b32 m0, s38
	s_nop 0
	global_load_lds_dwordx4 v154, s[36:37]
	s_mov_b32 m0, s39
	s_nop 0
	global_load_lds_dwordx4 v158, s[36:37]
	s_waitcnt vmcnt(8)
	s_waitcnt lgkmcnt(0)
	s_barrier
	s_setprio 1
	v_mfma_f32_16x16x32_bf16 v[62:65], v[130:133], v[184:187], v[62:65]
	v_mfma_f32_16x16x32_bf16 v[62:65], v[134:137], v[192:195], v[62:65]
	v_mfma_f32_16x16x32_bf16 v[58:61], v[138:141], v[184:187], v[58:61]
	v_mfma_f32_16x16x32_bf16 v[58:61], v[142:145], v[192:195], v[58:61]
	v_mfma_f32_16x16x32_bf16 v[54:57], v[146:149], v[184:187], v[54:57]
	v_mfma_f32_16x16x32_bf16 v[54:57], v[150:153], v[192:195], v[54:57]
	v_mfma_f32_16x16x32_bf16 v[50:53], v[174:177], v[184:187], v[50:53]
	v_mfma_f32_16x16x32_bf16 v[50:53], v[178:181], v[192:195], v[50:53]
	v_mfma_f32_16x16x32_bf16 v[46:49], v[130:133], v[196:199], v[46:49]
	v_mfma_f32_16x16x32_bf16 v[46:49], v[134:137], v[200:203], v[46:49]
	v_mfma_f32_16x16x32_bf16 v[42:45], v[138:141], v[196:199], v[42:45]
	v_mfma_f32_16x16x32_bf16 v[42:45], v[142:145], v[200:203], v[42:45]
	v_mfma_f32_16x16x32_bf16 v[38:41], v[146:149], v[196:199], v[38:41]
	v_mfma_f32_16x16x32_bf16 v[38:41], v[150:153], v[200:203], v[38:41]
	v_mfma_f32_16x16x32_bf16 v[34:37], v[174:177], v[196:199], v[34:37]
	v_mfma_f32_16x16x32_bf16 v[34:37], v[178:181], v[200:203], v[34:37]
	v_mfma_f32_16x16x32_bf16 v[30:33], v[130:133], v[204:207], v[30:33]
	v_mfma_f32_16x16x32_bf16 v[30:33], v[134:137], v[208:211], v[30:33]
	v_mfma_f32_16x16x32_bf16 v[26:29], v[138:141], v[204:207], v[26:29]
	v_mfma_f32_16x16x32_bf16 v[26:29], v[142:145], v[208:211], v[26:29]
	v_mfma_f32_16x16x32_bf16 v[22:25], v[146:149], v[204:207], v[22:25]
	v_mfma_f32_16x16x32_bf16 v[22:25], v[150:153], v[208:211], v[22:25]
	v_mfma_f32_16x16x32_bf16 v[18:21], v[174:177], v[204:207], v[18:21]
	v_mfma_f32_16x16x32_bf16 v[18:21], v[178:181], v[208:211], v[18:21]
	v_mfma_f32_16x16x32_bf16 v[14:17], v[130:133], v[212:215], v[14:17]
	v_mfma_f32_16x16x32_bf16 v[14:17], v[134:137], v[216:219], v[14:17]
	v_mfma_f32_16x16x32_bf16 v[10:13], v[138:141], v[212:215], v[10:13]
	v_mfma_f32_16x16x32_bf16 v[10:13], v[142:145], v[216:219], v[10:13]
	v_mfma_f32_16x16x32_bf16 v[6:9], v[146:149], v[212:215], v[6:9]
	v_mfma_f32_16x16x32_bf16 v[6:9], v[150:153], v[216:219], v[6:9]
	v_mfma_f32_16x16x32_bf16 v[2:5], v[174:177], v[212:215], v[2:5]
	v_mfma_f32_16x16x32_bf16 v[2:5], v[178:181], v[216:219], v[2:5]
	s_setprio 0
	s_barrier
	s_add_i32 s63, 0, 0x18000
	s_add_i32 s65, 0, 0x1c000
	v_add_u32_e32 v142, s63, v1
	v_add_u32_e32 v178, s65, v1
	ds_read_b128 v[130:133], v142
	ds_read_b128 v[134:137], v142 offset:1024
	ds_read_b128 v[138:141], v142 offset:2048
	ds_read_b128 v[142:145], v142 offset:3072
	ds_read_b128 v[146:149], v178
	ds_read_b128 v[150:153], v178 offset:1024
	ds_read_b128 v[174:177], v178 offset:2048
	ds_read_b128 v[178:181], v178 offset:3072
	s_add_u32 s36, s36, 0x2b0000
	s_addc_u32 s37, s37, 0
	s_mov_b32 m0, s40
	ds_read_b128 v[184:187], v189 offset:32768
	ds_read_b128 v[192:195], v189 offset:33792
	ds_read_b128 v[196:199], v189 offset:34816
	ds_read_b128 v[200:203], v189 offset:35840
	ds_read_b128 v[204:207], v189 offset:36864
	ds_read_b128 v[208:211], v189 offset:37888
	ds_read_b128 v[212:215], v189 offset:38912
	ds_read_b128 v[216:219], v189 offset:39936
	global_load_lds_dwordx4 v154, s[36:37]
	s_mov_b32 m0, s41
	s_nop 0
	global_load_lds_dwordx4 v158, s[36:37]
	s_waitcnt vmcnt(8)
	s_waitcnt lgkmcnt(0)
	s_barrier
	s_setprio 1
	v_mfma_f32_16x16x32_bf16 v[126:129], v[130:133], v[184:187], v[126:129]
	v_mfma_f32_16x16x32_bf16 v[126:129], v[134:137], v[192:195], v[126:129]
	v_mfma_f32_16x16x32_bf16 v[122:125], v[138:141], v[184:187], v[122:125]
	v_mfma_f32_16x16x32_bf16 v[122:125], v[142:145], v[192:195], v[122:125]
	v_mfma_f32_16x16x32_bf16 v[118:121], v[146:149], v[184:187], v[118:121]
	v_mfma_f32_16x16x32_bf16 v[118:121], v[150:153], v[192:195], v[118:121]
	v_mfma_f32_16x16x32_bf16 v[114:117], v[174:177], v[184:187], v[114:117]
	v_mfma_f32_16x16x32_bf16 v[114:117], v[178:181], v[192:195], v[114:117]
	v_mfma_f32_16x16x32_bf16 v[110:113], v[130:133], v[196:199], v[110:113]
	v_mfma_f32_16x16x32_bf16 v[110:113], v[134:137], v[200:203], v[110:113]
	v_mfma_f32_16x16x32_bf16 v[106:109], v[138:141], v[196:199], v[106:109]
	v_mfma_f32_16x16x32_bf16 v[106:109], v[142:145], v[200:203], v[106:109]
	v_mfma_f32_16x16x32_bf16 v[102:105], v[146:149], v[196:199], v[102:105]
	v_mfma_f32_16x16x32_bf16 v[102:105], v[150:153], v[200:203], v[102:105]
	v_mfma_f32_16x16x32_bf16 v[98:101], v[174:177], v[196:199], v[98:101]
	v_mfma_f32_16x16x32_bf16 v[98:101], v[178:181], v[200:203], v[98:101]
	v_mfma_f32_16x16x32_bf16 v[94:97], v[130:133], v[204:207], v[94:97]
	v_mfma_f32_16x16x32_bf16 v[94:97], v[134:137], v[208:211], v[94:97]
	v_mfma_f32_16x16x32_bf16 v[90:93], v[138:141], v[204:207], v[90:93]
	v_mfma_f32_16x16x32_bf16 v[90:93], v[142:145], v[208:211], v[90:93]
	v_mfma_f32_16x16x32_bf16 v[86:89], v[146:149], v[204:207], v[86:89]
	v_mfma_f32_16x16x32_bf16 v[86:89], v[150:153], v[208:211], v[86:89]
	v_mfma_f32_16x16x32_bf16 v[82:85], v[174:177], v[204:207], v[82:85]
	v_mfma_f32_16x16x32_bf16 v[82:85], v[178:181], v[208:211], v[82:85]
	v_mfma_f32_16x16x32_bf16 v[78:81], v[130:133], v[212:215], v[78:81]
	v_mfma_f32_16x16x32_bf16 v[78:81], v[134:137], v[216:219], v[78:81]
	v_mfma_f32_16x16x32_bf16 v[74:77], v[138:141], v[212:215], v[74:77]
	v_mfma_f32_16x16x32_bf16 v[74:77], v[142:145], v[216:219], v[74:77]
	v_mfma_f32_16x16x32_bf16 v[70:73], v[146:149], v[212:215], v[70:73]
	v_mfma_f32_16x16x32_bf16 v[70:73], v[150:153], v[216:219], v[70:73]
	v_mfma_f32_16x16x32_bf16 v[66:69], v[174:177], v[212:215], v[66:69]
	v_mfma_f32_16x16x32_bf16 v[66:69], v[178:181], v[216:219], v[66:69]
	s_setprio 0
	s_barrier
	s_add_i32 s36, s63, s35
	s_mov_b32 m0, s36
	ds_read_b128 v[184:187], v189 offset:49152
	ds_read_b128 v[192:195], v189 offset:50176
	ds_read_b128 v[196:199], v189 offset:51200
	ds_read_b128 v[200:203], v189 offset:52224
	ds_read_b128 v[204:207], v189 offset:53248
	ds_read_b128 v[208:211], v189 offset:54272
	ds_read_b128 v[212:215], v189 offset:55296
	ds_read_b128 v[216:219], v189 offset:56320
	global_load_lds_dwordx4 v156, s[98:99]
	s_add_i32 m0, s36, 0x2000
	s_add_u32 s28, s28, 0x2b0080
	s_addc_u32 s29, s29, 0
	s_add_i32 s36, s65, s35
	global_load_lds_dwordx4 v160, s[98:99]
	s_mov_b32 m0, s36
	s_nop 0
	global_load_lds_dwordx4 v156, s[28:29]
	s_add_i32 m0, s36, 0x2000
	s_nop 0
	global_load_lds_dwordx4 v160, s[28:29]
	s_mov_b32 m0, s43
	s_nop 0
	global_load_lds_dwordx4 v154, s[100:101]
	s_mov_b32 m0, s44
	s_nop 0
	global_load_lds_dwordx4 v158, s[100:101]
	s_waitcnt vmcnt(8)
	s_waitcnt lgkmcnt(0)
	s_barrier
	s_setprio 1
	v_mfma_f32_16x16x32_bf16 v[62:65], v[130:133], v[184:187], v[62:65]
	v_mfma_f32_16x16x32_bf16 v[62:65], v[134:137], v[192:195], v[62:65]
	v_mfma_f32_16x16x32_bf16 v[58:61], v[138:141], v[184:187], v[58:61]
	v_mfma_f32_16x16x32_bf16 v[58:61], v[142:145], v[192:195], v[58:61]
	v_mfma_f32_16x16x32_bf16 v[54:57], v[146:149], v[184:187], v[54:57]
	v_mfma_f32_16x16x32_bf16 v[54:57], v[150:153], v[192:195], v[54:57]
	v_mfma_f32_16x16x32_bf16 v[50:53], v[174:177], v[184:187], v[50:53]
	v_mfma_f32_16x16x32_bf16 v[50:53], v[178:181], v[192:195], v[50:53]
	v_mfma_f32_16x16x32_bf16 v[46:49], v[130:133], v[196:199], v[46:49]
	v_mfma_f32_16x16x32_bf16 v[46:49], v[134:137], v[200:203], v[46:49]
	v_mfma_f32_16x16x32_bf16 v[42:45], v[138:141], v[196:199], v[42:45]
	v_mfma_f32_16x16x32_bf16 v[42:45], v[142:145], v[200:203], v[42:45]
	v_mfma_f32_16x16x32_bf16 v[38:41], v[146:149], v[196:199], v[38:41]
	v_mfma_f32_16x16x32_bf16 v[38:41], v[150:153], v[200:203], v[38:41]
	v_mfma_f32_16x16x32_bf16 v[34:37], v[174:177], v[196:199], v[34:37]
	v_mfma_f32_16x16x32_bf16 v[34:37], v[178:181], v[200:203], v[34:37]
	v_mfma_f32_16x16x32_bf16 v[30:33], v[130:133], v[204:207], v[30:33]
	v_mfma_f32_16x16x32_bf16 v[30:33], v[134:137], v[208:211], v[30:33]
	v_mfma_f32_16x16x32_bf16 v[26:29], v[138:141], v[204:207], v[26:29]
	v_mfma_f32_16x16x32_bf16 v[26:29], v[142:145], v[208:211], v[26:29]
	v_mfma_f32_16x16x32_bf16 v[22:25], v[146:149], v[204:207], v[22:25]
	v_mfma_f32_16x16x32_bf16 v[22:25], v[150:153], v[208:211], v[22:25]
	v_mfma_f32_16x16x32_bf16 v[18:21], v[174:177], v[204:207], v[18:21]
	v_mfma_f32_16x16x32_bf16 v[18:21], v[178:181], v[208:211], v[18:21]
	v_mfma_f32_16x16x32_bf16 v[14:17], v[130:133], v[212:215], v[14:17]
	v_mfma_f32_16x16x32_bf16 v[14:17], v[134:137], v[216:219], v[14:17]
	v_mfma_f32_16x16x32_bf16 v[10:13], v[138:141], v[212:215], v[10:13]
	v_mfma_f32_16x16x32_bf16 v[10:13], v[142:145], v[216:219], v[10:13]
	v_mfma_f32_16x16x32_bf16 v[6:9], v[146:149], v[212:215], v[6:9]
	v_mfma_f32_16x16x32_bf16 v[6:9], v[150:153], v[216:219], v[6:9]
	v_mfma_f32_16x16x32_bf16 v[2:5], v[174:177], v[212:215], v[2:5]
	v_mfma_f32_16x16x32_bf16 v[2:5], v[178:181], v[216:219], v[2:5]
	s_setprio 0
	s_barrier
	s_add_i32 s62, s62, 2
	s_add_u32 s26, s26, 0x100
	s_addc_u32 s27, s27, 0
	s_add_u32 s12, s12, 0x100
	s_addc_u32 s59, s59, 0
	s_cmpk_gt_u32 s62, 0xa9
	s_cbranch_scc0 .LBB0_2805
	s_and_b64 vcc, exec, s[22:23]
	s_cbranch_vccz .LBB0_2808
	s_barrier
